# adds: scan-loop raw-row conversions deferred behind the matrix part (P2x, P2y RWKV loops), LDS read batching at sub-chunk heads, hand-written P8 fast path
# speedup vs baseline: 1.0814x; 1.0193x over previous
.LBB0_556:
	s_waitcnt lgkmcnt(0)
	s_barrier
	ds_read2st64_b32 v[184:185], v162 offset0:86 offset1:87
	ds_read2st64_b32 v[186:187], v162 offset0:88 offset1:89
	ds_read2st64_b32 v[188:189], v162 offset0:90 offset1:91
	ds_read_b32 v190, v162 offset:23552
	s_waitcnt lgkmcnt(0)
	s_and_b64 vcc, exec, s[38:39]
	v_add_f32_e32 v16, 0, v184
	v_cndmask_b32_e64 v16, v16, 0, s[4:5]
	v_cndmask_b32_e64 v17, 0, v185, s[10:11]
	v_add_f32_e32 v18, v16, v17
	v_cndmask_b32_e64 v16, 0, v186, s[12:13]
	v_add_f32_e32 v16, v18, v16
	v_cndmask_b32_e64 v17, 0, v187, s[14:15]
	v_add_f32_e32 v18, v16, v17
	v_cndmask_b32_e64 v16, 0, v188, s[16:17]
	v_add_f32_e32 v16, v18, v16
	v_cndmask_b32_e64 v17, 0, v189, s[18:19]
	v_add_f32_e32 v16, v16, v17
	v_cndmask_b32_e64 v17, 0, v190, s[20:21]
	v_add_f32_e32 v16, v16, v17
	v_mov_b32_e32 v17, 0
	s_cbranch_vccnz .LBB0_558
	v_and_b32_e32 v25, 0xffff0000, v77
	v_lshlrev_b32_e32 v24, 16, v77
	v_pk_add_f32 v[28:29], v[94:95], v[24:25] neg_lo:[0,1] neg_hi:[0,1]
	v_mov_b32_e32 v27, v25
	v_fmac_f32_e32 v27, v63, v29
	v_mov_b32_e32 v30, v24
	v_mul_f32_e32 v20, v65, v27
	s_waitcnt vmcnt(0)
	v_fmac_f32_e32 v30, v69, v28
	v_mul_f32_e32 v28, v20, v20
	ds_read_b32 v19, v137 offset:13824
	v_mul_f32_e32 v18, 0xbfb8aa3b, v16
	v_mov_b32_dpp v28, v28 quad_perm:[1,0,3,2] row_mask:0xf bank_mask:0xf bound_ctrl:1
	v_fmac_f32_e32 v28, v20, v20
	v_exp_f32_e32 v18, v18
	s_waitcnt lgkmcnt(0)
	v_add_f32_e32 v16, v16, v19
	v_add_f32_dpp v28, v28, v28 quad_perm:[2,3,0,1] row_mask:0xf bank_mask:0xf bound_ctrl:1
	v_mul_f32_e32 v19, 0xbfb8aa3b, v16
	v_exp_f32_e32 v21, v19
	v_add_f32_dpp v28, v28, v28 row_ror:4 row_mask:0xf bank_mask:0xf bound_ctrl:1
	v_mul_f32_e32 v19, 0x3fb8aa3b, v16
	v_lshlrev_b32_e32 v23, 16, v73
	v_add_f32_dpp v28, v28, v28 row_ror:8 row_mask:0xf bank_mask:0xf bound_ctrl:1
	v_exp_f32_e32 v22, v19
	v_readlane_b32 s3, v28, 16
	v_readlane_b32 s40, v28, 48
	v_readlane_b32 s0, v28, 0
	v_readlane_b32 s1, v28, 32
	v_mov_b32_e32 v28, s3
	v_mov_b32_e32 v29, s40
	v_pk_add_f32 v[28:29], s[0:1], v[28:29]
	v_sub_f32_e32 v19, v135, v23
	v_add_f32_e32 v28, v28, v29
	v_fma_f32 v19, v61, v19, v23
	v_rsq_f32_e32 v28, v28
	v_lshlrev_b32_e32 v26, 16, v79
	v_mov_b32_e32 v135, v23
	v_mov_b64_e32 v[94:95], v[24:25]
	v_min_f32_e32 v28, 0x5368d4a5, v28
	s_nop 0
	v_mul_f32_e32 v28, v20, v28
	v_xor_b32_e32 v20, 0x80000000, v28
	v_pk_mul_f32 v[18:19], v[18:19], v[20:21]
	s_nop 0
	v_cvt_pk_bf16_f32 v18, v18, v19
	v_add_f32_e32 v19, -1.0, v26
	v_fma_f32 v29, v67, v19, 1.0
	v_pk_mul_f32 v[20:21], v[28:29], v[26:27]
	s_nop 0
	v_pk_mul_f32 v[20:21], v[22:23], v[20:21] op_sel_hi:[0,1]
	v_bfe_u32 v22, v30, 16, 1
	v_cvt_pk_bf16_f32 v19, v20, v21
	v_add3_u32 v22, v30, v22, s51
	v_lshrrev_b32_e32 v20, 16, v18
	v_lshrrev_b32_e32 v21, 16, v19
	v_lshrrev_b32_e32 v22, 16, v22
	s_branch .LBB0_559

.LBB0_564:
	s_cmp_lt_u32 s2, 14
	s_cselect_b64 s[46:47], -1, 0
	s_cmp_gt_u32 s2, 13
	s_cbranch_scc1 .LBB0_569
	s_and_b64 vcc, exec, s[38:39]
	s_cbranch_vccnz .LBB0_571
	s_sub_i32 s0, s72, 18
	v_mad_i64_i32 v[16:17], s[0:1], s0, v132, v[92:93]
	global_load_ushort v195, v[16:17], off
	global_load_ushort v196, v[16:17], off offset:1024
	s_nop 0
	global_load_ushort v197, v[16:17], off offset:2048
	s_and_b64 vcc, exec, s[38:39]
	s_cbranch_vccz .LBB0_572

.LBB0_568:
	s_add_i32 s0, s72, -16
	s_ashr_i32 s1, s0, 31
	v_mad_i64_i32 v[16:17], s[40:41], s0, v132, v[92:93]
	s_lshl_b64 s[0:1], s[0:1], 10
	v_readlane_b32 s52, v250, 60
	global_load_ushort v71, v[16:17], off
	global_load_ushort v193, v[16:17], off offset:1024
	global_load_ushort v194, v[16:17], off offset:2048
	v_lshl_or_b32 v16, v90, 1, s0
	v_mov_b32_e32 v17, s1
	v_readlane_b32 s66, v249, 10
	v_readlane_b32 s67, v249, 11
	v_readlane_b32 s53, v250, 61
	v_readlane_b32 s54, v250, 62
	v_lshl_add_u64 v[18:19], s[66:67], 0, v[16:17]
	v_lshl_add_u64 v[16:17], s[90:91], 0, v[16:17]
	global_load_ushort v81, v[18:19], off
	global_load_ushort v85, v[16:17], off
	v_readlane_b32 s55, v250, 63
	v_readlane_b32 s56, v249, 0
	v_readlane_b32 s57, v249, 1
	v_readlane_b32 s58, v249, 2
	v_readlane_b32 s59, v249, 3
	v_readlane_b32 s60, v249, 4
	v_readlane_b32 s61, v249, 5
	v_readlane_b32 s62, v249, 6
	v_readlane_b32 s63, v249, 7
	v_readlane_b32 s64, v249, 8
	v_readlane_b32 s65, v249, 9

.LBB0_572:
	s_sub_i32 s0, s72, 17
	s_ashr_i32 s1, s0, 31
	v_mad_i64_i32 v[16:17], s[40:41], s0, v132, v[92:93]
	s_lshl_b64 s[0:1], s[0:1], 10
	v_readlane_b32 s52, v250, 60
	global_load_ushort v73, v[16:17], off
	global_load_ushort v191, v[16:17], off offset:1024
	global_load_ushort v192, v[16:17], off offset:2048
	v_lshl_or_b32 v16, v90, 1, s0
	v_mov_b32_e32 v17, s1
	v_readlane_b32 s66, v249, 10
	v_readlane_b32 s67, v249, 11
	v_readlane_b32 s53, v250, 61
	v_readlane_b32 s54, v250, 62
	v_lshl_add_u64 v[18:19], s[66:67], 0, v[16:17]
	v_lshl_add_u64 v[16:17], s[90:91], 0, v[16:17]
	global_load_ushort v75, v[18:19], off
	global_load_ushort v79, v[16:17], off
	v_readlane_b32 s55, v250, 63
	v_readlane_b32 s56, v249, 0
	v_readlane_b32 s57, v249, 1
	v_readlane_b32 s58, v249, 2
	v_readlane_b32 s59, v249, 3
	v_readlane_b32 s60, v249, 4
	v_readlane_b32 s61, v249, 5
	v_readlane_b32 s62, v249, 6
	v_readlane_b32 s63, v249, 7
	v_readlane_b32 s64, v249, 8
	v_readlane_b32 s65, v249, 9
	s_and_b64 vcc, exec, s[38:39]
	s_cbranch_vccz .LBB0_568
	s_branch .LBB0_569

.LBB0_584:
	s_waitcnt vmcnt(0)
	v_lshlrev_b32_e32 v135, 16, v195
	v_lshlrev_b32_e32 v95, 16, v196
	v_lshlrev_b32_e32 v94, 16, v197
	v_perm_b32 v77, v191, v192, s49
	v_perm_b32 v83, v193, v194, s49
	v_lshlrev_b32_e32 v16, 16, v89
	v_cndmask_b32_e64 v16, 0, v16, s[8:9]
	v_lshlrev_b32_e32 v17, 16, v138
	ds_write_b32 v137, v16 offset:17920
	v_add_f32_e32 v16, 0, v16
	v_cndmask_b32_e64 v17, 0, v17, s[8:9]
	v_add_f32_e32 v16, v17, v16
	ds_write_b32 v139, v17 offset:17920
	ds_write_b32 v163, v16 offset:24064
	s_waitcnt lgkmcnt(0)
	s_barrier
	ds_read2st64_b32 v[184:185], v162 offset0:94 offset1:95
	ds_read2st64_b32 v[186:187], v162 offset0:96 offset1:97
	ds_read2st64_b32 v[188:189], v162 offset0:98 offset1:99
	ds_read_b32 v190, v162 offset:25600
	s_waitcnt lgkmcnt(0)
	s_and_b64 vcc, exec, s[38:39]
	v_add_f32_e32 v16, 0, v184
	v_cndmask_b32_e64 v16, v16, 0, s[4:5]
	v_cndmask_b32_e64 v17, 0, v185, s[10:11]
	v_add_f32_e32 v18, v16, v17
	v_cndmask_b32_e64 v16, 0, v186, s[12:13]
	v_add_f32_e32 v16, v18, v16
	v_cndmask_b32_e64 v17, 0, v187, s[14:15]
	v_add_f32_e32 v18, v16, v17
	v_cndmask_b32_e64 v16, 0, v188, s[16:17]
	v_add_f32_e32 v16, v18, v16
	v_cndmask_b32_e64 v17, 0, v189, s[18:19]
	v_add_f32_e32 v16, v16, v17
	v_cndmask_b32_e64 v17, 0, v190, s[20:21]
	v_add_f32_e32 v16, v16, v17
	v_mov_b32_e32 v17, 0
	s_cbranch_vccnz .LBB0_586
	v_and_b32_e32 v25, 0xffff0000, v133
	v_lshlrev_b32_e32 v24, 16, v133
	v_pk_add_f32 v[28:29], v[96:97], v[24:25] neg_lo:[0,1] neg_hi:[0,1]
	v_mov_b32_e32 v27, v25
	v_fmac_f32_e32 v27, v63, v29
	v_mov_b32_e32 v30, v24
	v_mul_f32_e32 v20, v65, v27
	s_waitcnt vmcnt(0)
	v_fmac_f32_e32 v30, v69, v28
	v_mul_f32_e32 v28, v20, v20
	ds_read_b32 v19, v137 offset:17920
	v_mul_f32_e32 v18, 0xbfb8aa3b, v16
	v_mov_b32_dpp v28, v28 quad_perm:[1,0,3,2] row_mask:0xf bank_mask:0xf bound_ctrl:1
	v_fmac_f32_e32 v28, v20, v20
	v_exp_f32_e32 v18, v18
	s_waitcnt lgkmcnt(0)
	v_add_f32_e32 v16, v16, v19
	v_add_f32_dpp v28, v28, v28 quad_perm:[2,3,0,1] row_mask:0xf bank_mask:0xf bound_ctrl:1
	v_mul_f32_e32 v19, 0xbfb8aa3b, v16
	v_exp_f32_e32 v21, v19
	v_add_f32_dpp v28, v28, v28 row_ror:4 row_mask:0xf bank_mask:0xf bound_ctrl:1
	v_mul_f32_e32 v19, 0x3fb8aa3b, v16
	v_lshlrev_b32_e32 v23, 16, v87
	v_add_f32_dpp v28, v28, v28 row_ror:8 row_mask:0xf bank_mask:0xf bound_ctrl:1
	v_exp_f32_e32 v22, v19
	v_readlane_b32 s3, v28, 16
	v_readlane_b32 s52, v28, 48
	v_readlane_b32 s0, v28, 0
	v_readlane_b32 s1, v28, 32
	v_mov_b32_e32 v28, s3
	v_mov_b32_e32 v29, s52
	v_pk_add_f32 v[28:29], s[0:1], v[28:29]
	v_sub_f32_e32 v19, v142, v23
	v_add_f32_e32 v28, v28, v29
	v_fma_f32 v19, v61, v19, v23
	v_rsq_f32_e32 v28, v28
	v_lshlrev_b32_e32 v26, 16, v134
	v_mov_b32_e32 v142, v23
	v_mov_b64_e32 v[96:97], v[24:25]
	v_min_f32_e32 v28, 0x5368d4a5, v28
	s_nop 0
	v_mul_f32_e32 v28, v20, v28
	v_xor_b32_e32 v20, 0x80000000, v28
	v_pk_mul_f32 v[18:19], v[18:19], v[20:21]
	s_nop 0
	v_cvt_pk_bf16_f32 v18, v18, v19
	v_add_f32_e32 v19, -1.0, v26
	v_fma_f32 v29, v67, v19, 1.0
	v_pk_mul_f32 v[20:21], v[28:29], v[26:27]
	s_nop 0
	v_pk_mul_f32 v[20:21], v[22:23], v[20:21] op_sel_hi:[0,1]
	v_bfe_u32 v22, v30, 16, 1
	v_cvt_pk_bf16_f32 v19, v20, v21
	v_add3_u32 v22, v30, v22, s51
	v_lshrrev_b32_e32 v20, 16, v18
	v_lshrrev_b32_e32 v21, 16, v19
	v_lshrrev_b32_e32 v22, 16, v22
	s_branch .LBB0_587

.LBB0_592:
	s_cmp_gt_u32 s2, 12
	s_cbranch_scc1 .LBB0_597
	s_and_b64 vcc, exec, s[38:39]
	s_cbranch_vccnz .LBB0_599
	s_add_i32 s0, s72, -2
	v_mad_i64_i32 v[16:17], s[0:1], s0, v132, v[92:93]
	global_load_ushort v198, v[16:17], off
	global_load_ushort v199, v[16:17], off offset:1024
	s_nop 0
	global_load_ushort v200, v[16:17], off offset:2048
	s_and_b64 vcc, exec, s[38:39]
	s_cbranch_vccz .LBB0_600

.LBB0_596:
	s_ashr_i32 s73, s72, 31
	v_mad_i64_i32 v[16:17], s[0:1], s72, v132, v[92:93]
	s_lshl_b64 s[0:1], s[72:73], 10
	v_readlane_b32 s52, v250, 60
	global_load_ushort v46, v[16:17], off
	global_load_ushort v201, v[16:17], off offset:1024
	global_load_ushort v202, v[16:17], off offset:2048
	v_lshl_or_b32 v16, v90, 1, s0
	v_mov_b32_e32 v17, s1
	v_readlane_b32 s66, v249, 10
	v_readlane_b32 s67, v249, 11
	v_readlane_b32 s53, v250, 61
	v_readlane_b32 s54, v250, 62
	v_lshl_add_u64 v[18:19], s[66:67], 0, v[16:17]
	v_lshl_add_u64 v[16:17], s[90:91], 0, v[16:17]
	global_load_ushort v138, v[18:19], off
	global_load_ushort v141, v[16:17], off
	v_readlane_b32 s55, v250, 63
	v_readlane_b32 s56, v249, 0
	v_readlane_b32 s57, v249, 1
	v_readlane_b32 s58, v249, 2
	v_readlane_b32 s59, v249, 3
	v_readlane_b32 s60, v249, 4
	v_readlane_b32 s61, v249, 5
	v_readlane_b32 s62, v249, 6
	v_readlane_b32 s63, v249, 7
	v_readlane_b32 s64, v249, 8
	v_readlane_b32 s65, v249, 9

.LBB0_600:
	s_add_i32 s0, s72, -1
	s_ashr_i32 s1, s0, 31
	v_mad_i64_i32 v[16:17], s[42:43], s0, v132, v[92:93]
	s_lshl_b64 s[0:1], s[0:1], 10
	v_readlane_b32 s52, v250, 60
	global_load_ushort v87, v[16:17], off
	global_load_ushort v203, v[16:17], off offset:1024
	global_load_ushort v204, v[16:17], off offset:2048
	v_lshl_or_b32 v16, v90, 1, s0
	v_mov_b32_e32 v17, s1
	v_readlane_b32 s66, v249, 10
	v_readlane_b32 s67, v249, 11
	v_readlane_b32 s53, v250, 61
	v_readlane_b32 s54, v250, 62
	v_lshl_add_u64 v[18:19], s[66:67], 0, v[16:17]
	v_lshl_add_u64 v[16:17], s[90:91], 0, v[16:17]
	global_load_ushort v89, v[18:19], off
	global_load_ushort v134, v[16:17], off
	v_readlane_b32 s55, v250, 63
	v_readlane_b32 s56, v249, 0
	v_readlane_b32 s57, v249, 1
	v_readlane_b32 s58, v249, 2
	v_readlane_b32 s59, v249, 3
	v_readlane_b32 s60, v249, 4
	v_readlane_b32 s61, v249, 5
	v_readlane_b32 s62, v249, 6
	v_readlane_b32 s63, v249, 7
	v_readlane_b32 s64, v249, 8
	v_readlane_b32 s65, v249, 9
	s_and_b64 vcc, exec, s[38:39]
	s_cbranch_vccz .LBB0_596
	s_branch .LBB0_597

.LBB0_613:
	s_waitcnt vmcnt(0)
	v_lshlrev_b32_e32 v142, 16, v198
	v_lshlrev_b32_e32 v97, 16, v199
	v_lshlrev_b32_e32 v96, 16, v200
	v_perm_b32 v140, v201, v202, s49
	v_perm_b32 v133, v203, v204, s49
	v_lshlrev_b32_e32 v16, 16, v75
	v_cndmask_b32_e64 v16, 0, v16, s[8:9]
	v_lshlrev_b32_e32 v17, 16, v81
	ds_write_b32 v137, v16 offset:13824
	v_add_f32_e32 v16, 0, v16
	v_cndmask_b32_e64 v17, 0, v17, s[8:9]
	v_add_f32_e32 v16, v17, v16
	s_add_i32 s72, s72, 32
	s_add_i32 s2, s2, 2
	s_mov_b64 s[0:1], 0
	ds_write_b32 v139, v17 offset:13824
	ds_write_b32 v163, v16 offset:22016
	s_branch .LBB0_555

.LBB0_843:
	s_cmp_lt_u32 s42, 14
	s_cselect_b64 s[54:55], -1, 0
	s_cmp_gt_u32 s42, 13
	v_lshlrev_b32_e32 v28, 1, v138
	s_cbranch_scc1 .LBB0_845
	s_add_i32 s3, s59, s2
	s_add_i32 s0, s3, 31
	v_mad_i64_i32 v[16:17], s[0:1], s0, v173, v[140:141]
	s_add_i32 s0, s3, 32
	s_ashr_i32 s1, s0, 31
	v_mad_i64_i32 v[18:19], s[74:75], s0, v173, v[140:141]
	s_lshl_b64 s[0:1], s[0:1], 10
	global_load_ushort v251, v[16:17], off
	global_load_ushort v252, v[16:17], off offset:2048
	global_load_ushort v147, v[18:19], off
	global_load_ushort v157, v[18:19], off offset:1024
	global_load_ushort v174, v[18:19], off offset:2048
	global_load_ushort v253, v[16:17], off offset:1024
	v_or_b32_e32 v16, s0, v28
	v_mov_b32_e32 v17, s1
	s_add_i32 s0, s3, 33
	v_lshl_add_u64 v[18:19], s[62:63], 0, v[16:17]
	v_lshl_add_u64 v[16:17], s[90:91], 0, v[16:17]
	s_ashr_i32 s1, s0, 31
	global_load_ushort v175, v[18:19], off
	global_load_ushort v177, v[16:17], off
	v_mad_i64_i32 v[16:17], s[74:75], s0, v173, v[140:141]
	s_lshl_b64 s[0:1], s[0:1], 10
	global_load_ushort v181, v[16:17], off
	global_load_ushort v183, v[16:17], off offset:1024
	global_load_ushort v184, v[16:17], off offset:2048
	v_or_b32_e32 v16, s0, v28
	v_mov_b32_e32 v17, s1
	s_add_i32 s0, s3, 34
	v_lshl_add_u64 v[18:19], s[62:63], 0, v[16:17]
	v_lshl_add_u64 v[16:17], s[90:91], 0, v[16:17]
	s_ashr_i32 s1, s0, 31
	global_load_ushort v185, v[18:19], off
	global_load_ushort v186, v[16:17], off
	v_mad_i64_i32 v[16:17], s[74:75], s0, v173, v[140:141]
	s_lshl_b64 s[0:1], s[0:1], 10
	global_load_ushort v187, v[16:17], off
	global_load_ushort v188, v[16:17], off offset:1024
	global_load_ushort v189, v[16:17], off offset:2048
	v_or_b32_e32 v16, s0, v28
	v_mov_b32_e32 v17, s1
	s_add_i32 s0, s3, 35
	v_lshl_add_u64 v[18:19], s[62:63], 0, v[16:17]
	v_lshl_add_u64 v[16:17], s[90:91], 0, v[16:17]
	s_ashr_i32 s1, s0, 31
	global_load_ushort v193, v[18:19], off
	global_load_ushort v194, v[16:17], off
	v_mad_i64_i32 v[16:17], s[74:75], s0, v173, v[140:141]
	s_lshl_b64 s[0:1], s[0:1], 10
	global_load_ushort v195, v[16:17], off
	global_load_ushort v254, v[16:17], off offset:1024
	global_load_ushort v255, v[16:17], off offset:2048
	v_or_b32_e32 v16, s0, v28
	v_mov_b32_e32 v17, s1
	v_lshl_add_u64 v[18:19], s[62:63], 0, v[16:17]
	v_lshl_add_u64 v[16:17], s[90:91], 0, v[16:17]
	global_load_ushort v200, v[18:19], off
	global_load_ushort v202, v[16:17], off
.LBB0_845:
	v_add_u32_e32 v30, 0x1000, v83
	s_waitcnt lgkmcnt(0)
	s_barrier
	ds_read2_b64 v[42:45], v83 offset1:4
	ds_read2_b64 v[224:227], v30 offset0:64 offset1:68
	v_add_u32_e32 v29, 0x800, v83
	ds_read2_b64 v[22:25], v29 offset0:32 offset1:36
	ds_read2_b64 v[228:231], v83 offset0:8 offset1:12
	ds_read2_b64 v[236:239], v30 offset0:72 offset1:76
	v_add_u32_e32 v40, 0x1800, v83
	ds_read2_b64 v[244:247], v40 offset0:96 offset1:100
	ds_read2_b64 v[32:35], v29 offset0:40 offset1:44
	s_waitcnt lgkmcnt(5)
	v_mfma_f32_16x16x32_bf16 v[232:235], v[42:45], v[224:227], 0
	v_cvt_pk_bf16_f32 v16, v4, v5
	v_cvt_pk_bf16_f32 v17, v6, v7
	v_cvt_pk_bf16_f32 v18, v0, v1
	v_mfma_f32_16x16x32_bf16 v[240:243], v[224:227], v[42:45], 0
	v_cvt_pk_bf16_f32 v19, v2, v3
	ds_read_u16 v20, v69 offset:9216
	ds_read_u16 v21, v69 offset:9360
	ds_read_u16 v26, v69 offset:9504
	v_cvt_pk_bf16_f32 v36, v8, v9
	s_waitcnt lgkmcnt(7)
	v_mfma_f32_16x16x32_bf16 v[224:227], v[224:227], v[22:25], 0
	v_cvt_pk_bf16_f32 v37, v10, v11
	s_waitcnt lgkmcnt(1)
	v_lshl_or_b32 v20, v21, 16, v20
	v_cvt_pk_bf16_f32 v38, v12, v13
	v_mfma_f32_16x16x32_bf16 v[232:235], v[228:231], v[236:239], v[232:235]
	v_cvt_pk_bf16_f32 v39, v14, v15
	v_add_u32_e32 v222, 0x3400, v81
	v_mfma_f32_16x16x32_bf16 v[240:243], v[236:239], v[228:231], v[240:243]
	v_mfma_f32_16x16x32_bf16 v[224:227], v[236:239], v[32:35], v[224:227]
	ds_read_u16 v27, v69 offset:9648
	ds_read2_b64 v[236:239], v40 offset0:104 offset1:108
	s_nop 4
	v_cndmask_b32_e64 v46, 0, v240, s[24:25]
	v_cndmask_b32_e64 v47, 0, v241, s[30:31]
	v_mfma_f32_16x16x32_bf16 v[148:151], v[22:25], v[16:19], 0
	s_waitcnt lgkmcnt(1)
	v_lshl_or_b32 v21, v27, 16, v26
	v_cndmask_b32_e64 v152, 0, v242, s[34:35]
	v_cndmask_b32_e64 v31, 0, v232, s[22:23]
	v_mfma_f32_16x16x32_bf16 v[16:19], v[42:45], v[16:19], 0
	v_cndmask_b32_e64 v41, v233, 0, s[24:25]
	v_mfma_f32_16x16x32_bf16 v[42:45], v[244:247], v[42:45], 0
	s_waitcnt lgkmcnt(0)
	v_mfma_f32_16x16x32_bf16 v[42:45], v[236:239], v[228:231], v[42:45]
	v_mfma_f32_16x16x32_bf16 v[16:19], v[228:231], v[36:39], v[16:19]
	v_mfma_f32_16x16x32_bf16 v[148:151], v[32:35], v[36:39], v[148:151]
	s_nop 5
	v_cndmask_b32_e64 v26, 0, v42, s[24:25]
	v_cndmask_b32_e64 v27, 0, v43, s[30:31]
	v_cndmask_b32_e64 v42, 0, v44, s[34:35]
	v_cndmask_b32_e64 v43, 0, v45, s[36:37]
	v_cvt_pk_bf16_f32 v26, v26, v27
	v_cvt_pk_bf16_f32 v27, v42, v43
	v_cndmask_b32_e64 v36, 0, v243, s[36:37]
	v_cvt_pk_bf16_f32 v42, v46, v47
	v_cvt_pk_bf16_f32 v43, v152, v36
	v_mfma_f32_16x16x16_bf16 v[16:19], v[26:27], v[20:21], v[16:19]
	v_cndmask_b32_e64 v36, 0, v234, s[26:27]
	s_nop 6
	v_cvt_pk_bf16_f32 v26, v16, v17
	v_cvt_pk_bf16_f32 v27, v18, v19
	s_nop 1
	v_mfma_f32_16x16x16_bf16 v[16:19], v[42:43], v[26:27], v[16:19]
	v_cndmask_b32_e64 v27, 0, v235, s[28:29]
	v_cvt_pk_bf16_f32 v26, v31, v41
	v_cvt_pk_bf16_f32 v27, v36, v27
	v_cndmask_b32_e64 v31, v224, 0, s[22:23]
	s_nop 0
	v_mfma_f32_16x16x16_bf16 v[36:39], v[42:43], v[26:27], 0
	v_mfma_f32_16x16x16_bf16 v[42:45], v[26:27], v[42:43], 0
	s_nop 7
	v_cvt_pk_bf16_f32 v26, v42, v43
	v_cvt_pk_bf16_f32 v27, v44, v45
	v_cvt_pk_bf16_f32 v42, v16, v17
	v_cvt_pk_bf16_f32 v43, v18, v19
	s_nop 1
	v_mfma_f32_16x16x16_bf16 v[16:19], v[26:27], v[42:43], v[16:19]
	v_cvt_pk_bf16_f32 v42, v36, v37
	v_cvt_pk_bf16_f32 v43, v38, v39
	s_nop 1
	v_mfma_f32_16x16x16_bf16 v[36:39], v[26:27], v[42:43], 0
	s_nop 7
	v_cvt_pk_bf16_f32 v44, v36, v37
	v_cvt_pk_bf16_f32 v45, v38, v39
	v_mfma_f32_16x16x16_bf16 v[36:39], v[42:43], v[26:27], 0
	v_cvt_pk_bf16_f32 v42, v16, v17
	v_cvt_pk_bf16_f32 v43, v18, v19
	s_nop 5
	v_cvt_pk_bf16_f32 v26, v36, v37
	v_cvt_pk_bf16_f32 v27, v38, v39
	s_nop 1
	v_mfma_f32_16x16x16_bf16 v[36:39], v[44:45], v[26:27], 0
	v_mfma_f32_16x16x16_bf16 v[16:19], v[26:27], v[42:43], v[16:19]
	s_nop 6
	v_cvt_pk_bf16_f32 v36, v36, v37
	v_cvt_pk_bf16_f32 v37, v38, v39
	v_cvt_pk_bf16_f32 v26, v16, v17
	v_cvt_pk_bf16_f32 v27, v18, v19
	v_cndmask_b32_e64 v38, v227, 0, s[28:29]
	s_nop 0
	v_mfma_f32_16x16x16_bf16 v[16:19], v[36:37], v[26:27], v[16:19]
	v_cndmask_b32_e64 v36, 0, v225, s[24:25]
	v_cndmask_b32_e64 v37, v226, 0, s[26:27]
	v_cvt_pk_bf16_f32 v36, v31, v36
	v_mfma_f32_16x16x32_bf16 v[24:27], v[244:247], v[22:25], 0
	v_cvt_pk_bf16_f32 v37, v37, v38
	s_nop 2
	v_cvt_pk_bf16_f32 v22, v16, v17
	v_cvt_pk_bf16_f32 v23, v18, v19
	v_mfma_f32_16x16x32_bf16 v[24:27], v[236:239], v[32:35], v[24:27]
	s_nop 0
	v_mfma_f32_16x16x16_bf16 v[16:19], v[36:37], v[22:23], v[148:151]
	s_nop 2
	v_add_u32_e32 v148, s2, v210
	s_nop 1
	v_cndmask_b32_e64 v24, v24, 0, s[22:23]
	v_cndmask_b32_e64 v25, 0, v25, s[24:25]
	v_cndmask_b32_e64 v26, v26, 0, s[26:27]
	v_cndmask_b32_e64 v27, v27, 0, s[28:29]
	v_cvt_pk_bf16_f32 v24, v24, v25
	v_cvt_pk_bf16_f32 v25, v26, v27
	v_ashrrev_i32_e32 v149, 31, v148
	s_nop 0
	v_mfma_f32_16x16x16_bf16 v[16:19], v[24:25], v[20:21], v[16:19]
	s_nop 7
	v_bfe_u32 v24, v16, 16, 1
	v_add3_u32 v16, v16, v24, s94
	v_lshlrev_b64 v[24:25], 10, v[148:149]
	v_lshl_add_u64 v[24:25], v[142:143], 0, v[24:25]
	global_store_short_d16_hi v[24:25], v16, off
	v_bfe_u32 v16, v17, 16, 1
	v_add3_u32 v24, v17, v16, s94
	v_add_u32_e32 v16, 1, v148
	v_ashrrev_i32_e32 v17, 31, v16
	v_lshlrev_b64 v[16:17], 10, v[16:17]
	v_lshl_add_u64 v[16:17], v[142:143], 0, v[16:17]
	global_store_short_d16_hi v[16:17], v24, off
	v_bfe_u32 v16, v18, 16, 1
	v_add3_u32 v18, v18, v16, s94
	v_add_u32_e32 v16, 2, v148
	v_ashrrev_i32_e32 v17, 31, v16
	v_lshlrev_b64 v[16:17], 10, v[16:17]
	v_lshl_add_u64 v[16:17], v[142:143], 0, v[16:17]
	global_store_short_d16_hi v[16:17], v18, off
	v_bfe_u32 v16, v19, 16, 1
	v_add3_u32 v26, v19, v16, s94
	v_add_u32_e32 v149, s33, v182
	ds_read_u16 v25, v79 offset:4752
	ds_read_b128 v[16:19], v149 offset:13568
	ds_read_u16 v27, v79 offset:4608
	ds_read2_b32 v[32:33], v222 offset0:64 offset1:80
	v_add_u32_e32 v24, 3, v148
	s_waitcnt lgkmcnt(3)
	v_lshlrev_b32_e32 v35, 16, v25
	ds_read_u16 v25, v79 offset:5040
	ds_read_u16 v31, v79 offset:4896
	s_waitcnt lgkmcnt(3)
	v_lshlrev_b32_e32 v34, 16, v27
	v_pk_mul_f32 v[4:5], v[4:5], v[16:17]
	ds_read_u16 v16, v79 offset:6912
	s_waitcnt lgkmcnt(2)
	v_lshlrev_b32_e32 v37, 16, v25
	s_waitcnt lgkmcnt(1)
	v_lshlrev_b32_e32 v36, 16, v31
	ds_read_u16 v25, v79 offset:7056
	v_pk_mul_f32 v[34:35], v[32:33], v[34:35] op_sel_hi:[0,1]
	v_pk_mul_f32 v[36:37], v[32:33], v[36:37] op_sel_hi:[0,1]
	v_cvt_pk_bf16_f32 v34, v34, v35
	v_cvt_pk_bf16_f32 v35, v36, v37
	v_pk_mul_f32 v[6:7], v[6:7], v[18:19]
	ds_read_u16 v18, v79 offset:7344
	ds_read_u16 v19, v79 offset:7200
	s_waitcnt lgkmcnt(2)
	v_lshlrev_b32_e32 v17, 16, v25
	v_lshlrev_b32_e32 v16, 16, v16
	v_pk_mul_f32 v[16:17], v[32:33], v[16:17] op_sel_hi:[0,1]
	v_mfma_f32_16x16x16_bf16 v[4:7], v[34:35], v[22:23], v[4:7]
	v_cvt_pk_bf16_f32 v34, v16, v17
	s_waitcnt lgkmcnt(1)
	v_lshlrev_b32_e32 v17, 16, v18
	s_waitcnt lgkmcnt(0)
	v_lshlrev_b32_e32 v16, 16, v19
	v_pk_mul_f32 v[16:17], v[32:33], v[16:17] op_sel_hi:[0,1]
	v_cvt_pk_bf16_f32 v35, v16, v17
	ds_read_b128 v[16:19], v149 offset:13632
	ds_read_u16 v27, v79 offset:4784
	ds_read_u16 v31, v79 offset:4640
	v_ashrrev_i32_e32 v25, 31, v24
	v_mfma_f32_16x16x16_bf16 v[4:7], v[34:35], v[20:21], v[4:7]
	s_waitcnt lgkmcnt(2)
	v_pk_mul_f32 v[2:3], v[2:3], v[18:19]
	ds_read_u16 v19, v79 offset:5072
	v_pk_mul_f32 v[0:1], v[0:1], v[16:17]
	s_waitcnt lgkmcnt(2)
	v_lshlrev_b32_e32 v17, 16, v27
	s_waitcnt lgkmcnt(1)
	v_lshlrev_b32_e32 v16, 16, v31
	v_mov_b32_e32 v18, v33
	ds_read_u16 v27, v79 offset:4928
	s_waitcnt lgkmcnt(1)
	v_pk_mul_f32 v[16:17], v[18:19], v[16:17] op_sel_hi:[0,1]
	v_lshlrev_b32_e32 v33, 16, v19
	ds_read_u16 v19, v79 offset:7088
	v_cvt_pk_bf16_f32 v16, v16, v17
	s_waitcnt lgkmcnt(1)
	v_lshlrev_b32_e32 v32, 16, v27
	ds_read_u16 v27, v79 offset:6944
	s_waitcnt lgkmcnt(1)
	v_pk_mul_f32 v[32:33], v[18:19], v[32:33] op_sel_hi:[0,1]
	v_cvt_pk_bf16_f32 v17, v32, v33
	v_lshlrev_b32_e32 v33, 16, v19
	ds_read_u16 v19, v79 offset:7376
	ds_read_u16 v31, v79 offset:7232
	s_waitcnt lgkmcnt(2)
	v_lshlrev_b32_e32 v32, 16, v27
	v_mfma_f32_16x16x16_bf16 v[0:3], v[16:17], v[22:23], v[0:3]
	s_waitcnt lgkmcnt(1)
	v_pk_mul_f32 v[32:33], v[18:19], v[32:33] op_sel_hi:[0,1]
	v_cvt_pk_bf16_f32 v36, v32, v33
	v_lshlrev_b32_e32 v33, 16, v19
	s_waitcnt lgkmcnt(0)
	v_lshlrev_b32_e32 v32, 16, v31
	v_pk_mul_f32 v[18:19], v[18:19], v[32:33] op_sel_hi:[0,1]
	v_cvt_pk_bf16_f32 v37, v18, v19
	v_lshlrev_b64 v[16:17], 10, v[24:25]
	ds_read_b128 v[32:35], v149 offset:13696
	ds_read_u16 v18, v79 offset:4816
	ds_read2_b32 v[24:25], v222 offset0:96 offset1:112
	ds_read_u16 v27, v79 offset:4672
	ds_read_u16 v31, v79 offset:5104
	v_lshl_add_u64 v[16:17], v[142:143], 0, v[16:17]
	s_waitcnt lgkmcnt(3)
	v_lshlrev_b32_e32 v19, 16, v18
	v_pk_mul_f32 v[8:9], v[8:9], v[32:33]
	s_waitcnt lgkmcnt(1)
	v_lshlrev_b32_e32 v18, 16, v27
	ds_read_u16 v27, v79 offset:4960
	s_waitcnt lgkmcnt(1)
	v_lshlrev_b32_e32 v33, 16, v31
	ds_read_u16 v31, v79 offset:7120
	v_pk_mul_f32 v[18:19], v[24:25], v[18:19] op_sel_hi:[0,1]
	v_pk_mul_f32 v[10:11], v[10:11], v[34:35]
	s_waitcnt lgkmcnt(1)
	v_lshlrev_b32_e32 v32, 16, v27
	v_pk_mul_f32 v[32:33], v[24:25], v[32:33] op_sel_hi:[0,1]
	v_cvt_pk_bf16_f32 v18, v18, v19
	ds_read_u16 v27, v79 offset:6976
	v_cvt_pk_bf16_f32 v19, v32, v33
	s_waitcnt lgkmcnt(1)
	v_lshlrev_b32_e32 v33, 16, v31
	ds_read_u16 v31, v79 offset:7408
	ds_read_u16 v34, v79 offset:7264
	v_mfma_f32_16x16x16_bf16 v[8:11], v[18:19], v[22:23], v[8:11]
	s_waitcnt lgkmcnt(2)
	v_lshlrev_b32_e32 v32, 16, v27
	s_waitcnt lgkmcnt(1)
	v_lshlrev_b32_e32 v35, 16, v31
	s_waitcnt lgkmcnt(0)
	v_lshlrev_b32_e32 v34, 16, v34
	v_pk_mul_f32 v[32:33], v[24:25], v[32:33] op_sel_hi:[0,1]
	v_pk_mul_f32 v[34:35], v[24:25], v[34:35] op_sel_hi:[0,1]
	v_cvt_pk_bf16_f32 v32, v32, v33
	v_cvt_pk_bf16_f32 v33, v34, v35
	ds_read_u16 v24, v79 offset:4848
	ds_read_u16 v31, v79 offset:4704
	global_store_short_d16_hi v[16:17], v26, off
	v_mfma_f32_16x16x16_bf16 v[8:11], v[32:33], v[20:21], v[8:11]
	ds_read_b128 v[16:19], v149 offset:13760
	s_waitcnt lgkmcnt(1)
	v_lshlrev_b32_e32 v26, 16, v31
	ds_read_u16 v31, v79 offset:5136
	ds_read_u16 v32, v79 offset:4992
	v_lshlrev_b32_e32 v27, 16, v24
	v_mov_b32_e32 v24, v25
	v_pk_mul_f32 v[26:27], v[24:25], v[26:27] op_sel_hi:[0,1]
	s_waitcnt lgkmcnt(1)
	v_lshlrev_b32_e32 v33, 16, v31
	s_waitcnt lgkmcnt(0)
	v_lshlrev_b32_e32 v32, 16, v32
	v_pk_mul_f32 v[32:33], v[24:25], v[32:33] op_sel_hi:[0,1]
	v_cvt_pk_bf16_f32 v26, v26, v27
	v_cvt_pk_bf16_f32 v27, v32, v33
	v_pk_mul_f32 v[12:13], v[12:13], v[16:17]
	v_pk_mul_f32 v[14:15], v[14:15], v[18:19]
	ds_read_u16 v25, v79 offset:7152
	ds_read_u16 v16, v79 offset:7008
	v_mfma_f32_16x16x16_bf16 v[12:15], v[26:27], v[22:23], v[12:15]
	ds_read_u16 v18, v79 offset:7440
	ds_read_u16 v22, v79 offset:7296
	v_lshlrev_b32_e32 v27, 16, v191
	s_waitcnt lgkmcnt(3)
	v_lshlrev_b32_e32 v17, 16, v25
	s_waitcnt lgkmcnt(2)
	v_lshlrev_b32_e32 v16, 16, v16
	s_waitcnt lgkmcnt(1)
	v_lshlrev_b32_e32 v19, 16, v18
	s_waitcnt lgkmcnt(0)
	v_lshlrev_b32_e32 v18, 16, v22
	v_pk_mul_f32 v[16:17], v[24:25], v[16:17] op_sel_hi:[0,1]
	v_pk_mul_f32 v[18:19], v[24:25], v[18:19] op_sel_hi:[0,1]
	v_cvt_pk_bf16_f32 v16, v16, v17
	v_cvt_pk_bf16_f32 v17, v18, v19
	v_lshlrev_b32_e32 v18, 16, v196
	ds_write_b32 v203, v18 offset:17920
	v_add_f32_e32 v18, 0, v18
	v_lshlrev_b32_e32 v19, 16, v205
	ds_write_b32 v204, v19 offset:17920
	v_add_f32_e32 v18, v18, v19
	v_lshlrev_b32_e32 v19, 16, v215
	ds_write_b32 v207, v19 offset:17920
	v_add_f32_e32 v18, v18, v19
	s_waitcnt vmcnt(4)
	v_lshlrev_b32_e32 v146, 16, v251
	v_lshlrev_b32_e32 v144, 16, v252
	v_lshlrev_b32_e32 v145, 16, v253
	v_perm_b32 v221, v254, v255, s96
	v_lshlrev_b32_e32 v19, 16, v218
	v_add_f32_e32 v18, v18, v19
	ds_write_b32 v211, v19 offset:17920
	ds_write_b32 v67, v18 offset:24064
	s_waitcnt lgkmcnt(0)
	s_barrier
	ds_read2st64_b32 v[18:19], v65 offset0:94 offset1:95
	v_mfma_f32_16x16x16_bf16 v[12:15], v[16:17], v[20:21], v[12:15]
	ds_read_b32 v17, v65 offset:24576
	v_lshlrev_b32_e32 v26, 16, v190
	v_lshlrev_b32_e32 v31, 16, v192
	s_waitcnt lgkmcnt(1)
	v_add_f32_e32 v16, 0, v18
	v_cndmask_b32_e64 v18, 0, v19, s[40:41]
	ds_read_b32 v19, v203 offset:17920
	v_cndmask_b32_e64 v16, v16, 0, s[84:85]
	v_add_f32_e32 v16, v16, v18
	s_waitcnt lgkmcnt(1)
	v_cndmask_b32_e64 v17, 0, v17, s[38:39]
	v_add_f32_e32 v16, v16, v17
	v_mfma_f32_16x16x16_bf16 v[0:3], v[36:37], v[20:21], v[0:3]
	s_waitcnt lgkmcnt(0)
	v_add_f32_e32 v21, v19, v16
	v_mul_f32_e32 v17, 0xbfb8aa3b, v16
	v_mul_f32_e32 v16, 0xbfb8aa3b, v21
	v_exp_f32_e32 v18, v17
	v_exp_f32_e32 v17, v16
	v_mul_f32_e32 v16, 0x3fb8aa3b, v21
	v_exp_f32_e32 v20, v16
	v_sub_f32_e32 v16, v49, v27
	v_fma_f32 v23, v139, v16, v27
	v_mul_f32_e32 v16, v154, v23
	v_mul_f32_e32 v19, v16, v16
	v_lshlrev_b32_e32 v34, 16, v198
	v_lshlrev_b32_e32 v35, 16, v201
	v_mov_b32_dpp v19, v19 quad_perm:[1,0,3,2] row_mask:0xf bank_mask:0xf bound_ctrl:1
	v_fmac_f32_e32 v19, v16, v16
	v_and_b32_e32 v49, 0xffff0000, v220
	s_nop 0
	v_add_f32_dpp v19, v19, v19 quad_perm:[2,3,0,1] row_mask:0xf bank_mask:0xf bound_ctrl:1
	s_nop 1
	v_add_f32_dpp v19, v19, v19 row_ror:4 row_mask:0xf bank_mask:0xf bound_ctrl:1
	s_nop 1
	v_add_f32_dpp v19, v19, v19 row_ror:8 row_mask:0xf bank_mask:0xf bound_ctrl:1
	s_nop 0
	v_readlane_b32 s3, v19, 16
	v_readlane_b32 s43, v19, 48
	v_readlane_b32 s0, v19, 0
	v_readlane_b32 s1, v19, 32
	v_mov_b32_e32 v24, s3
	v_mov_b32_e32 v25, s43
	v_pk_add_f32 v[24:25], s[0:1], v[24:25]
	s_nop 0
	v_add_f32_e32 v19, v24, v25
	v_sub_f32_e32 v25, v223, v26
	v_rsq_f32_e32 v19, v19
	v_lshlrev_b32_e32 v22, 16, v197
	v_lshlrev_b32_e32 v223, 16, v217
	v_lshlrev_b32_e32 v33, 16, v199
	s_nop 0
	v_min_f32_e32 v24, 0x5368d4a5, v19
	v_fma_f32 v19, v51, v25, v26
	v_sub_f32_e32 v25, v56, v31
	v_fma_f32 v32, v156, v25, v31
	v_mul_f32_e32 v24, v16, v24
	v_xor_b32_e32 v16, 0x80000000, v24
	v_pk_mul_f32 v[18:19], v[18:19], v[16:17]
	v_lshlrev_b32_e32 v56, 16, v220
	v_cvt_pk_bf16_f32 v16, v18, v19
	v_add_f32_e32 v18, -1.0, v22
	v_fma_f32 v25, v155, v18, 1.0
	v_pk_mul_f32 v[18:19], v[24:25], v[22:23]
	v_sub_f32_e32 v24, v26, v34
	v_pk_mul_f32 v[18:19], v[20:21], v[18:19] op_sel_hi:[0,1]
	v_cvt_pk_bf16_f32 v18, v18, v19
	ds_write_b16 v71, v16
	ds_write_b16_d16_hi v71, v16 offset:2304
	ds_write_b16 v71, v18 offset:4608
	ds_read_b32 v16, v204 offset:17920
	ds_write_b16_d16_hi v71, v18 offset:6912
	v_bfe_u32 v18, v32, 16, 1
	v_add3_u32 v18, v32, v18, s94
	ds_write_b16_d16_hi v71, v18 offset:9216
	v_sub_f32_e32 v18, v27, v33
	s_waitcnt lgkmcnt(2)
	v_add_f32_e32 v32, v21, v16
	v_fma_f32 v21, v139, v18, v33
	v_mul_f32_e32 v18, v154, v21
	v_mul_f32_e32 v20, v18, v18
	v_mul_f32_e32 v16, 0xbfb8aa3b, v32
	v_exp_f32_e32 v19, v16
	v_mov_b32_dpp v20, v20 quad_perm:[1,0,3,2] row_mask:0xf bank_mask:0xf bound_ctrl:1
	v_fmac_f32_e32 v20, v18, v18
	v_mul_f32_e32 v16, 0x3fb8aa3b, v32
	v_exp_f32_e32 v16, v16
	v_add_f32_dpp v20, v20, v20 quad_perm:[2,3,0,1] row_mask:0xf bank_mask:0xf bound_ctrl:1
	s_nop 1
	v_add_f32_dpp v20, v20, v20 row_ror:4 row_mask:0xf bank_mask:0xf bound_ctrl:1
	s_nop 1
	v_add_f32_dpp v20, v20, v20 row_ror:8 row_mask:0xf bank_mask:0xf bound_ctrl:1
	s_nop 0
	v_readlane_b32 s3, v20, 16
	v_readlane_b32 s43, v20, 48
	v_readlane_b32 s0, v20, 0
	v_readlane_b32 s1, v20, 32
	v_mov_b32_e32 v22, s3
	v_mov_b32_e32 v23, s43
	v_pk_add_f32 v[22:23], s[0:1], v[22:23]
	s_nop 0
	v_add_f32_e32 v20, v22, v23
	v_rsq_f32_e32 v22, v20
	v_lshlrev_b32_e32 v20, 16, v206
	v_min_f32_e32 v22, 0x5368d4a5, v22
	v_fma_f32 v23, v51, v24, v34
	v_sub_f32_e32 v24, v31, v35
	v_fma_f32 v26, v156, v24, v35
	v_mul_f32_e32 v24, v18, v22
	v_mov_b32_e32 v22, v17
	v_add_f32_e32 v17, -1.0, v20
	v_xor_b32_e32 v18, 0x80000000, v24
	v_fma_f32 v25, v155, v17, 1.0
	v_pk_mul_f32 v[22:23], v[22:23], v[18:19]
	v_pk_mul_f32 v[20:21], v[24:25], v[20:21]
	v_cvt_pk_bf16_f32 v18, v22, v23
	v_pk_mul_f32 v[16:17], v[16:17], v[20:21] op_sel_hi:[0,1]
	v_cvt_pk_bf16_f32 v16, v16, v17
	ds_write_b16 v73, v18
	ds_write_b16_d16_hi v73, v18 offset:2304
	ds_write_b16 v73, v16 offset:4608
	ds_read_b32 v17, v207 offset:17920
	ds_write_b16_d16_hi v73, v16 offset:6912
	v_bfe_u32 v16, v26, 16, 1
	v_add3_u32 v16, v26, v16, s94
	ds_write_b16_d16_hi v73, v16 offset:9216
	s_waitcnt lgkmcnt(2)
	v_add_f32_e32 v22, v32, v17
	v_mul_f32_e32 v16, 0xbfb8aa3b, v22
	v_exp_f32_e32 v17, v16
	v_mul_f32_e32 v16, 0x3fb8aa3b, v22
	v_lshlrev_b32_e32 v21, 16, v213
	v_exp_f32_e32 v24, v16
	v_sub_f32_e32 v16, v33, v21
	v_fma_f32 v27, v139, v16, v21
	v_mul_f32_e32 v16, v154, v27
	v_mul_f32_e32 v20, v16, v16
	v_lshlrev_b32_e32 v18, 16, v212
	v_sub_f32_e32 v31, v34, v18
	v_mov_b32_dpp v20, v20 quad_perm:[1,0,3,2] row_mask:0xf bank_mask:0xf bound_ctrl:1
	v_fmac_f32_e32 v20, v16, v16
	v_lshlrev_b32_e32 v26, 16, v216
	v_sub_f32_e32 v21, v21, v49
	v_add_f32_dpp v20, v20, v20 quad_perm:[2,3,0,1] row_mask:0xf bank_mask:0xf bound_ctrl:1
	s_nop 1
	v_add_f32_dpp v20, v20, v20 row_ror:4 row_mask:0xf bank_mask:0xf bound_ctrl:1
	s_nop 1
	v_add_f32_dpp v20, v20, v20 row_ror:8 row_mask:0xf bank_mask:0xf bound_ctrl:1
	s_nop 0
	v_readlane_b32 s3, v20, 16
	v_readlane_b32 s43, v20, 48
	v_readlane_b32 s0, v20, 0
	v_readlane_b32 s1, v20, 32
	v_mov_b32_e32 v32, s3
	v_mov_b32_e32 v33, s43
	v_pk_add_f32 v[32:33], s[0:1], v[32:33]
	s_nop 0
	v_add_f32_e32 v20, v32, v33
	v_rsq_f32_e32 v23, v20
	v_lshlrev_b32_e32 v20, 16, v214
	v_fma_f32 v33, v51, v31, v18
	v_mov_b32_e32 v32, v19
	v_min_f32_e32 v25, 0x5368d4a5, v23
	v_sub_f32_e32 v23, v35, v20
	v_fma_f32 v23, v156, v23, v20
	v_sub_f32_e32 v18, v18, v223
	v_mul_f32_e32 v34, v16, v25
	v_xor_b32_e32 v16, 0x80000000, v34
	v_pk_mul_f32 v[32:33], v[32:33], v[16:17]
	v_add_f32_e32 v16, -1.0, v26
	v_fma_f32 v35, v155, v16, 1.0
	v_pk_mul_f32 v[26:27], v[34:35], v[26:27]
	v_cvt_pk_bf16_f32 v19, v32, v33
	v_pk_mul_f32 v[24:25], v[24:25], v[26:27] op_sel_hi:[0,1]
	v_cvt_pk_bf16_f32 v16, v24, v25
	ds_write_b16 v75, v19
	ds_write_b16_d16_hi v75, v19 offset:2304
	ds_write_b16 v75, v16 offset:4608
	ds_write_b16_d16_hi v75, v16 offset:6912
	v_bfe_u32 v16, v23, 16, 1
	v_add3_u32 v16, v23, v16, s94
	v_fma_f32 v23, v139, v21, v49
	v_mul_f32_e32 v26, v154, v23
	v_mul_f32_e32 v21, v26, v26
	ds_read_b32 v19, v211 offset:17920
	ds_write_b16_d16_hi v75, v16 offset:9216
	v_mov_b32_dpp v21, v21 quad_perm:[1,0,3,2] row_mask:0xf bank_mask:0xf bound_ctrl:1
	v_fmac_f32_e32 v21, v26, v26
	s_waitcnt lgkmcnt(1)
	v_add_f32_e32 v16, v22, v19
	v_add_f32_dpp v21, v21, v21 quad_perm:[2,3,0,1] row_mask:0xf bank_mask:0xf bound_ctrl:1
	v_mul_f32_e32 v19, 0xbfb8aa3b, v16
	v_exp_f32_e32 v19, v19
	v_add_f32_dpp v21, v21, v21 row_ror:4 row_mask:0xf bank_mask:0xf bound_ctrl:1
	v_mul_f32_e32 v16, 0x3fb8aa3b, v16
	v_exp_f32_e32 v16, v16
	v_add_f32_dpp v21, v21, v21 row_ror:8 row_mask:0xf bank_mask:0xf bound_ctrl:1
	s_nop 0
	v_readlane_b32 s3, v21, 16
	v_readlane_b32 s43, v21, 48
	v_readlane_b32 s0, v21, 0
	v_readlane_b32 s1, v21, 32
	v_mov_b32_e32 v24, s3
	v_mov_b32_e32 v25, s43
	v_pk_add_f32 v[24:25], s[0:1], v[24:25]
	s_nop 0
	v_add_f32_e32 v21, v24, v25
	v_rsq_f32_e32 v21, v21
	s_waitcnt vmcnt(4)
	v_lshlrev_b32_e32 v22, 16, v219
	v_min_f32_e32 v24, 0x5368d4a5, v21
	v_fma_f32 v21, v51, v18, v223
	v_sub_f32_e32 v18, v20, v56
	v_fma_f32 v27, v156, v18, v56
	v_mul_f32_e32 v24, v26, v24
	v_xor_b32_e32 v18, 0x80000000, v24
	v_mov_b32_e32 v20, v17
	v_add_f32_e32 v17, -1.0, v22
	v_pk_mul_f32 v[20:21], v[20:21], v[18:19]
	v_fma_f32 v25, v155, v17, 1.0
	v_cvt_pk_bf16_f32 v18, v20, v21
	v_pk_mul_f32 v[20:21], v[24:25], v[22:23]
	s_and_b64 vcc, exec, s[44:45]
	v_pk_mul_f32 v[16:17], v[16:17], v[20:21] op_sel_hi:[0,1]
	v_cvt_pk_bf16_f32 v16, v16, v17
	ds_write_b16 v77, v18
	ds_write_b16_d16_hi v77, v18 offset:2304
	ds_write_b16 v77, v16 offset:4608
	ds_write_b16_d16_hi v77, v16 offset:6912
	v_bfe_u32 v16, v27, 16, 1
	v_add3_u32 v16, v27, v16, s94
	ds_write_b16_d16_hi v77, v16 offset:9216
	s_cbranch_vccnz .LBB0_847
	ds_write_b32 v65, v19 offset:13568
.LBB0_847:
	s_cmp_gt_u32 s42, 12
	s_cbranch_scc1 .LBB0_849
	s_add_i32 s3, s59, s2
	s_add_i32 s0, s3, 47
	v_mad_i64_i32 v[16:17], s[0:1], s0, v173, v[140:141]
	s_add_i32 s0, s3, 48
	s_ashr_i32 s1, s0, 31
	v_mad_i64_i32 v[18:19], s[44:45], s0, v173, v[140:141]
	s_lshl_b64 s[0:1], s[0:1], 10
	global_load_ushort v251, v[16:17], off
	global_load_ushort v252, v[16:17], off offset:2048
	global_load_ushort v190, v[18:19], off
	global_load_ushort v191, v[18:19], off offset:1024
	global_load_ushort v192, v[18:19], off offset:2048
	global_load_ushort v253, v[16:17], off offset:1024
	v_or_b32_e32 v16, s0, v28
	v_mov_b32_e32 v17, s1
	s_add_i32 s0, s3, 49
	v_lshl_add_u64 v[18:19], s[62:63], 0, v[16:17]
	v_lshl_add_u64 v[16:17], s[90:91], 0, v[16:17]
	s_ashr_i32 s1, s0, 31
	global_load_ushort v196, v[18:19], off
	global_load_ushort v197, v[16:17], off
	v_mad_i64_i32 v[16:17], s[44:45], s0, v173, v[140:141]
	s_lshl_b64 s[0:1], s[0:1], 10
	global_load_ushort v198, v[16:17], off
	global_load_ushort v199, v[16:17], off offset:1024
	global_load_ushort v201, v[16:17], off offset:2048
	v_or_b32_e32 v16, s0, v28
	v_mov_b32_e32 v17, s1
	s_add_i32 s0, s3, 50
	v_lshl_add_u64 v[18:19], s[62:63], 0, v[16:17]
	v_lshl_add_u64 v[16:17], s[90:91], 0, v[16:17]
	s_ashr_i32 s1, s0, 31
	global_load_ushort v205, v[18:19], off
	global_load_ushort v206, v[16:17], off
	v_mad_i64_i32 v[16:17], s[44:45], s0, v173, v[140:141]
	s_lshl_b64 s[0:1], s[0:1], 10
	global_load_ushort v212, v[16:17], off
	global_load_ushort v213, v[16:17], off offset:1024
	global_load_ushort v214, v[16:17], off offset:2048
	v_or_b32_e32 v16, s0, v28
	v_mov_b32_e32 v17, s1
	s_add_i32 s0, s3, 51
	v_lshl_add_u64 v[18:19], s[62:63], 0, v[16:17]
	v_lshl_add_u64 v[16:17], s[90:91], 0, v[16:17]
	s_ashr_i32 s1, s0, 31
	global_load_ushort v215, v[18:19], off
	global_load_ushort v216, v[16:17], off
	v_mad_i64_i32 v[16:17], s[44:45], s0, v173, v[140:141]
	s_lshl_b64 s[0:1], s[0:1], 10
	global_load_ushort v217, v[16:17], off
	global_load_ushort v254, v[16:17], off offset:1024
	global_load_ushort v255, v[16:17], off offset:2048
	v_or_b32_e32 v16, s0, v28
	v_mov_b32_e32 v17, s1
	v_lshl_add_u64 v[18:19], s[62:63], 0, v[16:17]
	v_lshl_add_u64 v[16:17], s[90:91], 0, v[16:17]
	global_load_ushort v218, v[18:19], off
	global_load_ushort v219, v[16:17], off
.LBB0_849:
	s_waitcnt lgkmcnt(0)
	s_barrier
	ds_read2_b64 v[36:39], v30 offset0:64 offset1:68
	ds_read2_b64 v[224:227], v83 offset1:4
	ds_read2_b64 v[150:153], v30 offset0:72 offset1:76
	ds_read2_b64 v[228:231], v83 offset0:8 offset1:12
	ds_read2_b64 v[16:19], v29 offset0:32 offset1:36
	v_cvt_pk_bf16_f32 v44, v4, v5
	s_waitcnt lgkmcnt(3)
	v_mfma_f32_16x16x32_bf16 v[30:33], v[36:39], v[224:227], 0
	v_cvt_pk_bf16_f32 v45, v6, v7
	v_cvt_pk_bf16_f32 v46, v0, v1
	v_cvt_pk_bf16_f32 v47, v2, v3
	v_mfma_f32_16x16x32_bf16 v[24:27], v[224:227], v[36:39], 0
	v_cvt_pk_bf16_f32 v28, v8, v9
	s_andn2_b64 vcc, exec, s[54:55]
	s_mov_b64 s[0:1], -1
	s_waitcnt lgkmcnt(1)
	v_mfma_f32_16x16x32_bf16 v[236:239], v[150:153], v[228:231], v[30:33]
	s_nop 2
	ds_read2_b64 v[32:35], v40 offset0:96 offset1:100
	v_mfma_f32_16x16x32_bf16 v[232:235], v[228:231], v[150:153], v[24:27]
	v_cvt_pk_bf16_f32 v30, v12, v13
	v_cvt_pk_bf16_f32 v31, v14, v15
	s_nop 0
	v_cndmask_b32_e64 v236, 0, v236, s[24:25]
	ds_read2_b64 v[24:27], v29 offset0:40 offset1:44
	ds_read_u16 v240, v69 offset:9216
	ds_read_u16 v241, v69 offset:9360
	ds_read_u16 v242, v69 offset:9504
	ds_read2_b64 v[40:43], v40 offset0:104 offset1:108
	s_waitcnt lgkmcnt(6)
	v_mfma_f32_16x16x32_bf16 v[20:23], v[16:19], v[44:47], 0
	v_cvt_pk_bf16_f32 v29, v10, v11
	v_cndmask_b32_e64 v237, 0, v237, s[30:31]
	v_cndmask_b32_e64 v238, 0, v238, s[34:35]
	v_mfma_f32_16x16x32_bf16 v[44:47], v[224:227], v[44:47], 0
	v_cndmask_b32_e64 v232, 0, v232, s[22:23]
	v_cndmask_b32_e64 v233, v233, 0, s[24:25]
	s_waitcnt lgkmcnt(5)
	v_mfma_f32_16x16x32_bf16 v[224:227], v[32:35], v[224:227], 0
	v_mfma_f32_16x16x32_bf16 v[36:39], v[36:39], v[16:19], 0
	s_waitcnt lgkmcnt(0)
	v_mfma_f32_16x16x32_bf16 v[224:227], v[40:43], v[228:231], v[224:227]
	v_mfma_f32_16x16x32_bf16 v[36:39], v[150:153], v[24:27], v[36:39]
	ds_read_u16 v151, v69 offset:9648
	s_nop 5
	v_cndmask_b32_e64 v152, 0, v224, s[24:25]
	v_cndmask_b32_e64 v153, 0, v225, s[30:31]
	v_cndmask_b32_e64 v224, 0, v226, s[34:35]
	v_cndmask_b32_e64 v225, 0, v227, s[36:37]
	v_cvt_pk_bf16_f32 v152, v152, v153
	v_cvt_pk_bf16_f32 v153, v224, v225
	v_mfma_f32_16x16x32_bf16 v[44:47], v[228:231], v[28:31], v[44:47]
	v_lshl_or_b32 v150, v241, 16, v240
	s_waitcnt lgkmcnt(0)
	v_lshl_or_b32 v151, v151, 16, v242
	v_cndmask_b32_e64 v224, 0, v239, s[36:37]
	v_cvt_pk_bf16_f32 v228, v236, v237
	v_cvt_pk_bf16_f32 v229, v238, v224
	v_mfma_f32_16x16x16_bf16 v[44:47], v[152:153], v[150:151], v[44:47]
	v_cndmask_b32_e64 v224, 0, v234, s[26:27]
	v_cndmask_b32_e64 v36, v36, 0, s[22:23]
	v_cndmask_b32_e64 v37, 0, v37, s[24:25]
	v_mfma_f32_16x16x32_bf16 v[16:19], v[32:35], v[16:19], 0
	v_cndmask_b32_e64 v38, v38, 0, s[26:27]
	s_nop 2
	v_cvt_pk_bf16_f32 v152, v44, v45
	v_cvt_pk_bf16_f32 v153, v46, v47
	v_cndmask_b32_e64 v32, v39, 0, s[28:29]
	v_cvt_pk_bf16_f32 v36, v36, v37
	v_mfma_f32_16x16x16_bf16 v[44:47], v[228:229], v[152:153], v[44:47]
	v_cndmask_b32_e64 v153, 0, v235, s[28:29]
	v_cvt_pk_bf16_f32 v152, v232, v233
	v_cvt_pk_bf16_f32 v153, v224, v153
	v_cvt_pk_bf16_f32 v37, v38, v32
	v_mfma_f32_16x16x32_bf16 v[32:35], v[40:43], v[24:27], v[16:19]
	v_mfma_f32_16x16x16_bf16 v[224:227], v[228:229], v[152:153], 0
	v_mfma_f32_16x16x16_bf16 v[228:231], v[152:153], v[228:229], 0
	s_nop 5
	v_cndmask_b32_e64 v32, v32, 0, s[22:23]
	v_mfma_f32_16x16x32_bf16 v[18:21], v[24:27], v[28:31], v[20:23]
	v_cndmask_b32_e64 v24, v35, 0, s[28:29]
	v_cvt_pk_bf16_f32 v152, v228, v229
	v_cvt_pk_bf16_f32 v153, v230, v231
	v_cvt_pk_bf16_f32 v228, v44, v45
	v_cvt_pk_bf16_f32 v229, v46, v47
	v_cndmask_b32_e64 v22, 0, v33, s[24:25]
	v_cndmask_b32_e64 v23, v34, 0, s[26:27]
	v_mfma_f32_16x16x16_bf16 v[44:47], v[152:153], v[228:229], v[44:47]
	v_cvt_pk_bf16_f32 v228, v224, v225
	v_cvt_pk_bf16_f32 v229, v226, v227
	v_cvt_pk_bf16_f32 v22, v32, v22
	v_cvt_pk_bf16_f32 v23, v23, v24
	v_mfma_f32_16x16x16_bf16 v[224:227], v[152:153], v[228:229], 0
	s_nop 2
	v_cvt_pk_bf16_f32 v232, v44, v45
	v_cvt_pk_bf16_f32 v233, v46, v47
	s_nop 2
	v_cvt_pk_bf16_f32 v230, v224, v225
	v_cvt_pk_bf16_f32 v231, v226, v227
	v_mfma_f32_16x16x16_bf16 v[224:227], v[228:229], v[152:153], 0
	s_nop 7
	v_cvt_pk_bf16_f32 v228, v224, v225
	v_cvt_pk_bf16_f32 v229, v226, v227
	s_nop 1
	v_mfma_f32_16x16x16_bf16 v[224:227], v[230:231], v[228:229], 0
	v_mfma_f32_16x16x16_bf16 v[44:47], v[228:229], v[232:233], v[44:47]
	s_nop 6
	v_cvt_pk_bf16_f32 v152, v224, v225
	v_cvt_pk_bf16_f32 v153, v226, v227
	v_cvt_pk_bf16_f32 v224, v44, v45
	v_cvt_pk_bf16_f32 v225, v46, v47
	ds_read_u16 v226, v79 offset:4608
	s_nop 0
	v_mfma_f32_16x16x16_bf16 v[44:47], v[152:153], v[224:225], v[44:47]
	s_nop 7
	v_cvt_pk_bf16_f32 v16, v44, v45
	v_cvt_pk_bf16_f32 v17, v46, v47
	s_nop 1
	v_mfma_f32_16x16x16_bf16 v[18:21], v[36:37], v[16:17], v[18:21]
	ds_read_u16 v34, v79 offset:4640
	ds_read_u16 v35, v79 offset:4672
	ds_read_u16 v36, v79 offset:4704
	v_mfma_f32_16x16x16_bf16 v[18:21], v[22:23], v[150:151], v[18:21]
	v_add_u32_e32 v22, 16, v148
	s_nop 6
	v_bfe_u32 v23, v18, 16, 1
	v_add3_u32 v18, v18, v23, s94
	v_ashrrev_i32_e32 v23, 31, v22
	v_lshlrev_b64 v[22:23], 10, v[22:23]
	v_lshl_add_u64 v[22:23], v[142:143], 0, v[22:23]
	global_store_short_d16_hi v[22:23], v18, off
	v_bfe_u32 v18, v19, 16, 1
	v_add3_u32 v22, v19, v18, s94
	v_add_u32_e32 v18, 17, v148
	v_ashrrev_i32_e32 v19, 31, v18
	v_lshlrev_b64 v[18:19], 10, v[18:19]
	v_lshl_add_u64 v[18:19], v[142:143], 0, v[18:19]
	global_store_short_d16_hi v[18:19], v22, off
	ds_read_b128 v[22:25], v149 offset:13568
	ds_read2_b32 v[30:31], v222 offset0:64 offset1:80
	ds_read_b128 v[26:29], v149 offset:13632
	v_bfe_u32 v18, v20, 16, 1
	v_add3_u32 v37, v20, v18, s94
	ds_read_u16 v19, v79 offset:4752
	ds_read_u16 v20, v79 offset:4896
	ds_read_u16 v38, v79 offset:4784
	ds_read_u16 v39, v79 offset:4928
	ds_read_u16 v40, v79 offset:4816
	ds_read_u16 v41, v79 offset:4960
	ds_read_u16 v42, v79 offset:4992
	ds_read_u16 v43, v79 offset:4848
	s_waitcnt lgkmcnt(10)
	v_pk_mul_f32 v[6:7], v[6:7], v[24:25]
	v_pk_mul_f32 v[4:5], v[4:5], v[22:23]
	s_waitcnt lgkmcnt(7)
	v_lshlrev_b32_e32 v23, 16, v19
	v_lshlrev_b32_e32 v22, 16, v226
	ds_read_u16 v19, v79 offset:5040
	ds_read_u16 v32, v79 offset:6912
	ds_read_u16 v44, v79 offset:5072
	ds_read_u16 v45, v79 offset:6944
	ds_read_u16 v46, v79 offset:5104
	ds_read_u16 v47, v79 offset:6976
	ds_read_u16 v152, v79 offset:7008
	ds_read_u16 v153, v79 offset:5136
	s_waitcnt lgkmcnt(7)
	v_lshlrev_b32_e32 v25, 16, v19
	v_lshlrev_b32_e32 v24, 16, v20
	v_pk_mul_f32 v[22:23], v[30:31], v[22:23] op_sel_hi:[0,1]
	v_pk_mul_f32 v[24:25], v[30:31], v[24:25] op_sel_hi:[0,1]
	ds_read_u16 v19, v79 offset:7056
	ds_read_u16 v20, v79 offset:7200
	ds_read_u16 v224, v79 offset:7088
	ds_read_u16 v225, v79 offset:7232
	ds_read_u16 v226, v79 offset:7120
	ds_read_u16 v227, v79 offset:7264
	ds_read_u16 v228, v79 offset:7296
	ds_read_u16 v229, v79 offset:7152
	v_cvt_pk_bf16_f32 v22, v22, v23
	v_cvt_pk_bf16_f32 v23, v24, v25
	s_waitcnt lgkmcnt(7)
	v_lshlrev_b32_e32 v25, 16, v19
	ds_read_u16 v19, v79 offset:7344
	v_lshlrev_b32_e32 v24, 16, v32
	s_waitcnt lgkmcnt(7)
	v_lshlrev_b32_e32 v32, 16, v20
	v_pk_mul_f32 v[24:25], v[30:31], v[24:25] op_sel_hi:[0,1]
	v_cvt_pk_bf16_f32 v24, v24, v25
	s_waitcnt lgkmcnt(0)
	v_lshlrev_b32_e32 v33, 16, v19
	v_pk_mul_f32 v[32:33], v[30:31], v[32:33] op_sel_hi:[0,1]
	v_cvt_pk_bf16_f32 v25, v32, v33
	v_mfma_f32_16x16x16_bf16 v[4:7], v[22:23], v[16:17], v[4:7]
	v_lshlrev_b32_e32 v23, 16, v38
	v_lshlrev_b32_e32 v22, 16, v34
	v_mov_b32_e32 v20, v31
	v_mfma_f32_16x16x16_bf16 v[4:7], v[24:25], v[150:151], v[4:7]
	v_lshlrev_b32_e32 v25, 16, v44
	v_lshlrev_b32_e32 v24, 16, v39
	ds_read_u16 v230, v79 offset:7376
	ds_read_u16 v231, v79 offset:7408
	ds_read_u16 v232, v79 offset:7440
	v_pk_mul_f32 v[22:23], v[20:21], v[22:23] op_sel_hi:[0,1]
	v_pk_mul_f32 v[24:25], v[20:21], v[24:25] op_sel_hi:[0,1]
	v_cvt_pk_bf16_f32 v22, v22, v23
	v_cvt_pk_bf16_f32 v23, v24, v25
	v_lshlrev_b32_e32 v25, 16, v224
	v_lshlrev_b32_e32 v24, 16, v45
	v_pk_mul_f32 v[24:25], v[20:21], v[24:25] op_sel_hi:[0,1]
	v_pk_mul_f32 v[0:1], v[0:1], v[26:27]
	v_cvt_pk_bf16_f32 v26, v24, v25
	s_waitcnt lgkmcnt(2)
	v_lshlrev_b32_e32 v25, 16, v230
	v_lshlrev_b32_e32 v24, 16, v225
	v_pk_mul_f32 v[24:25], v[20:21], v[24:25] op_sel_hi:[0,1]
	v_add_u32_e32 v18, 18, v148
	v_pk_mul_f32 v[2:3], v[2:3], v[28:29]
	v_cvt_pk_bf16_f32 v27, v24, v25
	v_ashrrev_i32_e32 v19, 31, v18
	v_mfma_f32_16x16x16_bf16 v[0:3], v[22:23], v[16:17], v[0:3]
	v_lshlrev_b64 v[18:19], 10, v[18:19]
	v_lshl_add_u64 v[18:19], v[142:143], 0, v[18:19]
	ds_read_b128 v[22:25], v149 offset:13696
	global_store_short_d16_hi v[18:19], v37, off
	v_mfma_f32_16x16x16_bf16 v[0:3], v[26:27], v[150:151], v[0:3]
	ds_read2_b32 v[18:19], v222 offset0:96 offset1:112
	ds_read_b128 v[26:29], v149 offset:13760
	s_waitcnt lgkmcnt(4)
	v_lshlrev_b32_e32 v31, 16, v231
	s_waitcnt lgkmcnt(2)
	v_pk_mul_f32 v[10:11], v[10:11], v[24:25]
	v_pk_mul_f32 v[8:9], v[8:9], v[22:23]
	v_lshlrev_b32_e32 v23, 16, v40
	v_lshlrev_b32_e32 v22, 16, v35
	v_lshlrev_b32_e32 v25, 16, v46
	v_lshlrev_b32_e32 v24, 16, v41
	s_waitcnt lgkmcnt(1)
	v_pk_mul_f32 v[22:23], v[18:19], v[22:23] op_sel_hi:[0,1]
	v_pk_mul_f32 v[24:25], v[18:19], v[24:25] op_sel_hi:[0,1]
	v_cvt_pk_bf16_f32 v22, v22, v23
	v_cvt_pk_bf16_f32 v23, v24, v25
	v_lshlrev_b32_e32 v25, 16, v226
	v_lshlrev_b32_e32 v24, 16, v47
	v_lshlrev_b32_e32 v30, 16, v227
	v_pk_mul_f32 v[24:25], v[18:19], v[24:25] op_sel_hi:[0,1]
	v_pk_mul_f32 v[30:31], v[18:19], v[30:31] op_sel_hi:[0,1]
	v_cvt_pk_bf16_f32 v24, v24, v25
	v_cvt_pk_bf16_f32 v25, v30, v31
	v_mfma_f32_16x16x16_bf16 v[8:11], v[22:23], v[16:17], v[8:11]
	v_lshlrev_b32_e32 v23, 16, v43
	v_lshlrev_b32_e32 v22, 16, v36
	v_mov_b32_e32 v18, v19
	v_mfma_f32_16x16x16_bf16 v[8:11], v[24:25], v[150:151], v[8:11]
	v_lshlrev_b32_e32 v25, 16, v153
	v_lshlrev_b32_e32 v24, 16, v42
	v_pk_mul_f32 v[22:23], v[18:19], v[22:23] op_sel_hi:[0,1]
	v_pk_mul_f32 v[24:25], v[18:19], v[24:25] op_sel_hi:[0,1]
	v_cvt_pk_bf16_f32 v22, v22, v23
	v_cvt_pk_bf16_f32 v23, v24, v25
	s_waitcnt lgkmcnt(0)
	v_pk_mul_f32 v[12:13], v[12:13], v[26:27]
	v_lshlrev_b32_e32 v25, 16, v229
	v_lshlrev_b32_e32 v24, 16, v152
	v_lshlrev_b32_e32 v27, 16, v232
	v_lshlrev_b32_e32 v26, 16, v228
	v_pk_mul_f32 v[24:25], v[18:19], v[24:25] op_sel_hi:[0,1]
	v_pk_mul_f32 v[18:19], v[18:19], v[26:27] op_sel_hi:[0,1]
	v_pk_mul_f32 v[14:15], v[14:15], v[28:29]
	v_cvt_pk_bf16_f32 v24, v24, v25
	v_cvt_pk_bf16_f32 v25, v18, v19
	v_mfma_f32_16x16x16_bf16 v[12:15], v[22:23], v[16:17], v[12:15]
	v_bfe_u32 v20, v21, 16, 1
	v_add3_u32 v30, v21, v20, s94
	v_add_u32_e32 v20, 19, v148
	v_mfma_f32_16x16x16_bf16 v[12:15], v[24:25], v[150:151], v[12:15]
	v_ashrrev_i32_e32 v21, 31, v20
	v_lshlrev_b64 v[16:17], 10, v[20:21]
	v_lshl_add_u64 v[16:17], v[142:143], 0, v[16:17]
	global_store_short_d16_hi v[16:17], v30, off
	s_waitcnt vmcnt(4)
	v_lshlrev_b32_e32 v223, 16, v251
	v_lshlrev_b32_e32 v56, 16, v252
	v_lshlrev_b32_e32 v49, 16, v253
	v_perm_b32 v220, v254, v255, s96
	s_cbranch_vccnz .LBB0_840
	v_lshlrev_b32_e32 v16, 16, v175
	ds_write_b32 v203, v16 offset:13824
	v_add_f32_e32 v16, 0, v16
	v_lshlrev_b32_e32 v17, 16, v185
	ds_write_b32 v204, v17 offset:13824
	v_add_f32_e32 v16, v16, v17
	v_lshlrev_b32_e32 v17, 16, v193
	ds_write_b32 v207, v17 offset:13824
	v_add_f32_e32 v16, v16, v17
	v_lshlrev_b32_e32 v17, 16, v200
	v_add_f32_e32 v16, v16, v17
	s_add_i32 s2, s2, 32
	s_add_i32 s42, s42, 2
	s_mov_b64 s[0:1], 0
	ds_write_b32 v211, v17 offset:13824
	ds_write_b32 v67, v16 offset:22016
	s_branch .LBB0_840

.LBB0_1542:
	s_or_b64 exec, exec, s[0:1]
	v_readlane_b32 s0, v249, 56
	v_readlane_b32 s1, v249, 57
	s_and_b64 vcc, exec, s[0:1]
	s_waitcnt lgkmcnt(0)
	s_barrier
	s_cbranch_vccnz .LBB0_1553
	s_cmpk_lg_i32 s68, 0x800
	s_cbranch_scc1 .Lp8_orig
	v_readlane_b32 s12, v249, 8
	v_readlane_b32 s13, v249, 9
	v_readlane_b32 s14, v249, 10
	v_readlane_b32 s15, v249, 11
	v_mov_b32_e32 v179, 0
	v_mov_b32_e32 v177, 0
	v_lshl_add_u64 v[4:5], s[16:17], 0, v[178:179]
	s_nop 1
	v_lshl_add_u64 v[6:7], s[12:13], 0, v[176:177]
	v_lshl_add_u64 v[8:9], s[14:15], 0, v[176:177]
	global_load_dwordx4 v[100:103], v[6:7], off
	global_load_dwordx4 v[104:107], v[6:7], off offset:1024
	global_load_dwordx4 v[108:111], v[6:7], off offset:2048
	global_load_dwordx4 v[112:115], v[6:7], off offset:3072
	s_mov_b32 s20, 0
	s_add_i32 s20, s20, s70
	s_lshl_b32 s22, s20, 11
	s_mov_b32 s23, 0
	v_lshl_add_u64 v[10:11], v[4:5], 0, s[22:23]
	global_load_dwordx2 v[20:21], v[10:11], off
	global_load_dwordx2 v[22:23], v[10:11], off offset:512
	global_load_dwordx2 v[24:25], v[10:11], off offset:1024
	global_load_dwordx2 v[26:27], v[10:11], off offset:1536
	s_mul_i32 s20, s68, 1
	s_add_i32 s20, s20, s70
	s_lshl_b32 s22, s20, 11
	s_mov_b32 s23, 0
	v_lshl_add_u64 v[10:11], v[4:5], 0, s[22:23]
	global_load_dwordx2 v[28:29], v[10:11], off
	global_load_dwordx2 v[30:31], v[10:11], off offset:512
	global_load_dwordx2 v[32:33], v[10:11], off offset:1024
	global_load_dwordx2 v[34:35], v[10:11], off offset:1536
	s_mul_i32 s20, s68, 2
	s_add_i32 s20, s20, s70
	s_lshl_b32 s22, s20, 11
	s_mov_b32 s23, 0
	v_lshl_add_u64 v[10:11], v[4:5], 0, s[22:23]
	global_load_dwordx2 v[36:37], v[10:11], off
	global_load_dwordx2 v[38:39], v[10:11], off offset:512
	global_load_dwordx2 v[40:41], v[10:11], off offset:1024
	global_load_dwordx2 v[42:43], v[10:11], off offset:1536
	s_mul_i32 s20, s68, 3
	s_add_i32 s20, s20, s70
	s_lshl_b32 s22, s20, 11
	s_mov_b32 s23, 0
	v_lshl_add_u64 v[10:11], v[4:5], 0, s[22:23]
	global_load_dwordx2 v[44:45], v[10:11], off
	global_load_dwordx2 v[46:47], v[10:11], off offset:512
	global_load_dwordx2 v[48:49], v[10:11], off offset:1024
	global_load_dwordx2 v[50:51], v[10:11], off offset:1536
	s_mul_i32 s20, s68, 4
	s_add_i32 s20, s20, s70
	s_lshl_b32 s22, s20, 11
	s_mov_b32 s23, 0
	v_lshl_add_u64 v[10:11], v[4:5], 0, s[22:23]
	global_load_dwordx2 v[52:53], v[10:11], off
	global_load_dwordx2 v[54:55], v[10:11], off offset:512
	global_load_dwordx2 v[56:57], v[10:11], off offset:1024
	global_load_dwordx2 v[58:59], v[10:11], off offset:1536
	s_mul_i32 s20, s68, 5
	s_add_i32 s20, s20, s70
	s_lshl_b32 s22, s20, 11
	s_mov_b32 s23, 0
	v_lshl_add_u64 v[10:11], v[4:5], 0, s[22:23]
	global_load_dwordx2 v[60:61], v[10:11], off
	global_load_dwordx2 v[62:63], v[10:11], off offset:512
	global_load_dwordx2 v[64:65], v[10:11], off offset:1024
	global_load_dwordx2 v[66:67], v[10:11], off offset:1536
	s_mul_i32 s20, s68, 6
	s_add_i32 s20, s20, s70
	s_lshl_b32 s22, s20, 11
	s_mov_b32 s23, 0
	v_lshl_add_u64 v[10:11], v[4:5], 0, s[22:23]
	global_load_dwordx2 v[68:69], v[10:11], off
	global_load_dwordx2 v[70:71], v[10:11], off offset:512
	global_load_dwordx2 v[72:73], v[10:11], off offset:1024
	global_load_dwordx2 v[74:75], v[10:11], off offset:1536
	s_mul_i32 s20, s68, 7
	s_add_i32 s20, s20, s70
	s_lshl_b32 s22, s20, 11
	s_mov_b32 s23, 0
	v_lshl_add_u64 v[10:11], v[4:5], 0, s[22:23]
	global_load_dwordx2 v[76:77], v[10:11], off
	global_load_dwordx2 v[78:79], v[10:11], off offset:512
	global_load_dwordx2 v[80:81], v[10:11], off offset:1024
	global_load_dwordx2 v[82:83], v[10:11], off offset:1536
	s_cmpk_lt_i32 s70, 0x400
	s_cbranch_scc0 .Lp8_no9a
	s_mul_i32 s20, s68, 8
	s_add_i32 s20, s20, s70
	s_lshl_b32 s22, s20, 11
	s_mov_b32 s23, 0
	v_lshl_add_u64 v[10:11], v[4:5], 0, s[22:23]
	global_load_dwordx2 v[84:85], v[10:11], off
	global_load_dwordx2 v[86:87], v[10:11], off offset:512
	global_load_dwordx2 v[88:89], v[10:11], off offset:1024
	global_load_dwordx2 v[90:91], v[10:11], off offset:1536
.Lp8_no9a:
	v_mov_b32_e32 v12, 0x358637bd
	s_mov_b32 s24, 0x3a800000
	s_waitcnt vmcnt(28)
	v_lshlrev_b32_e32 v120, 16, v20
	v_and_b32_e32 v121, 0xffff0000, v20
	v_lshlrev_b32_e32 v122, 16, v21
	v_and_b32_e32 v123, 0xffff0000, v21
	v_lshlrev_b32_e32 v124, 16, v22
	v_and_b32_e32 v125, 0xffff0000, v22
	v_lshlrev_b32_e32 v126, 16, v23
	v_and_b32_e32 v127, 0xffff0000, v23
	v_lshlrev_b32_e32 v128, 16, v24
	v_and_b32_e32 v129, 0xffff0000, v24
	v_lshlrev_b32_e32 v130, 16, v25
	v_and_b32_e32 v131, 0xffff0000, v25
	v_lshlrev_b32_e32 v132, 16, v26
	v_and_b32_e32 v133, 0xffff0000, v26
	v_lshlrev_b32_e32 v134, 16, v27
	v_and_b32_e32 v135, 0xffff0000, v27
	v_mul_f32_e32 v136, v120, v120
	v_mul_f32_e32 v137, v124, v124
	v_mul_f32_e32 v138, v128, v128
	v_mul_f32_e32 v139, v132, v132
	v_fmac_f32_e32 v136, v121, v121
	v_fmac_f32_e32 v137, v125, v125
	v_fmac_f32_e32 v138, v129, v129
	v_fmac_f32_e32 v139, v133, v133
	v_fmac_f32_e32 v136, v122, v122
	v_fmac_f32_e32 v137, v126, v126
	v_fmac_f32_e32 v138, v130, v130
	v_fmac_f32_e32 v139, v134, v134
	v_fmac_f32_e32 v136, v123, v123
	v_fmac_f32_e32 v137, v127, v127
	v_fmac_f32_e32 v138, v131, v131
	v_fmac_f32_e32 v139, v135, v135
	v_add_f32_e32 v136, v136, v137
	v_add_f32_e32 v138, v138, v139
	v_add_f32_e32 v136, v136, v138
	s_nop 1
	v_add_f32_dpp v136, v136, v136 quad_perm:[1,0,3,2] row_mask:0xf bank_mask:0xf bound_ctrl:1
	s_nop 1
	v_add_f32_dpp v136, v136, v136 quad_perm:[2,3,0,1] row_mask:0xf bank_mask:0xf bound_ctrl:1
	s_nop 1
	v_add_f32_dpp v136, v136, v136 row_ror:4 row_mask:0xf bank_mask:0xf bound_ctrl:1
	s_nop 1
	v_add_f32_dpp v136, v136, v136 row_ror:8 row_mask:0xf bank_mask:0xf bound_ctrl:1
	s_nop 1
	v_readlane_b32 s0, v136, 0
	v_readlane_b32 s1, v136, 16
	v_readlane_b32 s2, v136, 32
	v_readlane_b32 s3, v136, 48
	s_nop 1
	v_mov_b32_e32 v137, s1
	v_mov_b32_e32 v138, s3
	v_add_f32_e32 v137, s0, v137
	v_add_f32_e32 v138, s2, v138
	v_add_f32_e32 v137, v137, v138
	v_fma_f32 v137, v137, s24, v12
	v_rsq_f32_e32 v137, v137
	s_mov_b32 s20, 0
	s_add_i32 s20, s20, s70
	s_lshl_b32 s22, s20, 12
	s_mov_b32 s23, 0
	v_lshl_add_u64 v[10:11], v[8:9], 0, s[22:23]
	v_mul_f32_e32 v140, v120, v137
	v_mul_f32_e32 v141, v121, v137
	v_mul_f32_e32 v142, v122, v137
	v_mul_f32_e32 v143, v123, v137
	v_mul_f32_e32 v144, v124, v137
	v_mul_f32_e32 v145, v125, v137
	v_mul_f32_e32 v146, v126, v137
	v_mul_f32_e32 v147, v127, v137
	v_mul_f32_e32 v148, v128, v137
	v_mul_f32_e32 v149, v129, v137
	v_mul_f32_e32 v150, v130, v137
	v_mul_f32_e32 v151, v131, v137
	v_mul_f32_e32 v152, v132, v137
	v_mul_f32_e32 v153, v133, v137
	v_mul_f32_e32 v154, v134, v137
	v_mul_f32_e32 v155, v135, v137
	v_mul_f32_e32 v140, v140, v100
	v_mul_f32_e32 v141, v141, v101
	v_mul_f32_e32 v142, v142, v102
	v_mul_f32_e32 v143, v143, v103
	v_mul_f32_e32 v144, v144, v104
	v_mul_f32_e32 v145, v145, v105
	v_mul_f32_e32 v146, v146, v106
	v_mul_f32_e32 v147, v147, v107
	v_mul_f32_e32 v148, v148, v108
	v_mul_f32_e32 v149, v149, v109
	v_mul_f32_e32 v150, v150, v110
	v_mul_f32_e32 v151, v151, v111
	v_mul_f32_e32 v152, v152, v112
	v_mul_f32_e32 v153, v153, v113
	v_mul_f32_e32 v154, v154, v114
	v_mul_f32_e32 v155, v155, v115
	global_store_dwordx4 v[10:11], v[140:143], off
	global_store_dwordx4 v[10:11], v[144:147], off offset:1024
	global_store_dwordx4 v[10:11], v[148:151], off offset:2048
	global_store_dwordx4 v[10:11], v[152:155], off offset:3072
	s_waitcnt vmcnt(28)
	v_lshlrev_b32_e32 v120, 16, v28
	v_and_b32_e32 v121, 0xffff0000, v28
	v_lshlrev_b32_e32 v122, 16, v29
	v_and_b32_e32 v123, 0xffff0000, v29
	v_lshlrev_b32_e32 v124, 16, v30
	v_and_b32_e32 v125, 0xffff0000, v30
	v_lshlrev_b32_e32 v126, 16, v31
	v_and_b32_e32 v127, 0xffff0000, v31
	v_lshlrev_b32_e32 v128, 16, v32
	v_and_b32_e32 v129, 0xffff0000, v32
	v_lshlrev_b32_e32 v130, 16, v33
	v_and_b32_e32 v131, 0xffff0000, v33
	v_lshlrev_b32_e32 v132, 16, v34
	v_and_b32_e32 v133, 0xffff0000, v34
	v_lshlrev_b32_e32 v134, 16, v35
	v_and_b32_e32 v135, 0xffff0000, v35
	v_mul_f32_e32 v136, v120, v120
	v_mul_f32_e32 v137, v124, v124
	v_mul_f32_e32 v138, v128, v128
	v_mul_f32_e32 v139, v132, v132
	v_fmac_f32_e32 v136, v121, v121
	v_fmac_f32_e32 v137, v125, v125
	v_fmac_f32_e32 v138, v129, v129
	v_fmac_f32_e32 v139, v133, v133
	v_fmac_f32_e32 v136, v122, v122
	v_fmac_f32_e32 v137, v126, v126
	v_fmac_f32_e32 v138, v130, v130
	v_fmac_f32_e32 v139, v134, v134
	v_fmac_f32_e32 v136, v123, v123
	v_fmac_f32_e32 v137, v127, v127
	v_fmac_f32_e32 v138, v131, v131
	v_fmac_f32_e32 v139, v135, v135
	v_add_f32_e32 v136, v136, v137
	v_add_f32_e32 v138, v138, v139
	v_add_f32_e32 v136, v136, v138
	s_nop 1
	v_add_f32_dpp v136, v136, v136 quad_perm:[1,0,3,2] row_mask:0xf bank_mask:0xf bound_ctrl:1
	s_nop 1
	v_add_f32_dpp v136, v136, v136 quad_perm:[2,3,0,1] row_mask:0xf bank_mask:0xf bound_ctrl:1
	s_nop 1
	v_add_f32_dpp v136, v136, v136 row_ror:4 row_mask:0xf bank_mask:0xf bound_ctrl:1
	s_nop 1
	v_add_f32_dpp v136, v136, v136 row_ror:8 row_mask:0xf bank_mask:0xf bound_ctrl:1
	s_nop 1
	v_readlane_b32 s0, v136, 0
	v_readlane_b32 s1, v136, 16
	v_readlane_b32 s2, v136, 32
	v_readlane_b32 s3, v136, 48
	s_nop 1
	v_mov_b32_e32 v137, s1
	v_mov_b32_e32 v138, s3
	v_add_f32_e32 v137, s0, v137
	v_add_f32_e32 v138, s2, v138
	v_add_f32_e32 v137, v137, v138
	v_fma_f32 v137, v137, s24, v12
	v_rsq_f32_e32 v137, v137
	s_mul_i32 s20, s68, 1
	s_add_i32 s20, s20, s70
	s_lshl_b32 s22, s20, 12
	s_mov_b32 s23, 0
	v_lshl_add_u64 v[10:11], v[8:9], 0, s[22:23]
	v_mul_f32_e32 v140, v120, v137
	v_mul_f32_e32 v141, v121, v137
	v_mul_f32_e32 v142, v122, v137
	v_mul_f32_e32 v143, v123, v137
	v_mul_f32_e32 v144, v124, v137
	v_mul_f32_e32 v145, v125, v137
	v_mul_f32_e32 v146, v126, v137
	v_mul_f32_e32 v147, v127, v137
	v_mul_f32_e32 v148, v128, v137
	v_mul_f32_e32 v149, v129, v137
	v_mul_f32_e32 v150, v130, v137
	v_mul_f32_e32 v151, v131, v137
	v_mul_f32_e32 v152, v132, v137
	v_mul_f32_e32 v153, v133, v137
	v_mul_f32_e32 v154, v134, v137
	v_mul_f32_e32 v155, v135, v137
	v_mul_f32_e32 v140, v140, v100
	v_mul_f32_e32 v141, v141, v101
	v_mul_f32_e32 v142, v142, v102
	v_mul_f32_e32 v143, v143, v103
	v_mul_f32_e32 v144, v144, v104
	v_mul_f32_e32 v145, v145, v105
	v_mul_f32_e32 v146, v146, v106
	v_mul_f32_e32 v147, v147, v107
	v_mul_f32_e32 v148, v148, v108
	v_mul_f32_e32 v149, v149, v109
	v_mul_f32_e32 v150, v150, v110
	v_mul_f32_e32 v151, v151, v111
	v_mul_f32_e32 v152, v152, v112
	v_mul_f32_e32 v153, v153, v113
	v_mul_f32_e32 v154, v154, v114
	v_mul_f32_e32 v155, v155, v115
	global_store_dwordx4 v[10:11], v[140:143], off
	global_store_dwordx4 v[10:11], v[144:147], off offset:1024
	global_store_dwordx4 v[10:11], v[148:151], off offset:2048
	global_store_dwordx4 v[10:11], v[152:155], off offset:3072
	s_waitcnt vmcnt(28)
	v_lshlrev_b32_e32 v120, 16, v36
	v_and_b32_e32 v121, 0xffff0000, v36
	v_lshlrev_b32_e32 v122, 16, v37
	v_and_b32_e32 v123, 0xffff0000, v37
	v_lshlrev_b32_e32 v124, 16, v38
	v_and_b32_e32 v125, 0xffff0000, v38
	v_lshlrev_b32_e32 v126, 16, v39
	v_and_b32_e32 v127, 0xffff0000, v39
	v_lshlrev_b32_e32 v128, 16, v40
	v_and_b32_e32 v129, 0xffff0000, v40
	v_lshlrev_b32_e32 v130, 16, v41
	v_and_b32_e32 v131, 0xffff0000, v41
	v_lshlrev_b32_e32 v132, 16, v42
	v_and_b32_e32 v133, 0xffff0000, v42
	v_lshlrev_b32_e32 v134, 16, v43
	v_and_b32_e32 v135, 0xffff0000, v43
	v_mul_f32_e32 v136, v120, v120
	v_mul_f32_e32 v137, v124, v124
	v_mul_f32_e32 v138, v128, v128
	v_mul_f32_e32 v139, v132, v132
	v_fmac_f32_e32 v136, v121, v121
	v_fmac_f32_e32 v137, v125, v125
	v_fmac_f32_e32 v138, v129, v129
	v_fmac_f32_e32 v139, v133, v133
	v_fmac_f32_e32 v136, v122, v122
	v_fmac_f32_e32 v137, v126, v126
	v_fmac_f32_e32 v138, v130, v130
	v_fmac_f32_e32 v139, v134, v134
	v_fmac_f32_e32 v136, v123, v123
	v_fmac_f32_e32 v137, v127, v127
	v_fmac_f32_e32 v138, v131, v131
	v_fmac_f32_e32 v139, v135, v135
	v_add_f32_e32 v136, v136, v137
	v_add_f32_e32 v138, v138, v139
	v_add_f32_e32 v136, v136, v138
	s_nop 1
	v_add_f32_dpp v136, v136, v136 quad_perm:[1,0,3,2] row_mask:0xf bank_mask:0xf bound_ctrl:1
	s_nop 1
	v_add_f32_dpp v136, v136, v136 quad_perm:[2,3,0,1] row_mask:0xf bank_mask:0xf bound_ctrl:1
	s_nop 1
	v_add_f32_dpp v136, v136, v136 row_ror:4 row_mask:0xf bank_mask:0xf bound_ctrl:1
	s_nop 1
	v_add_f32_dpp v136, v136, v136 row_ror:8 row_mask:0xf bank_mask:0xf bound_ctrl:1
	s_nop 1
	v_readlane_b32 s0, v136, 0
	v_readlane_b32 s1, v136, 16
	v_readlane_b32 s2, v136, 32
	v_readlane_b32 s3, v136, 48
	s_nop 1
	v_mov_b32_e32 v137, s1
	v_mov_b32_e32 v138, s3
	v_add_f32_e32 v137, s0, v137
	v_add_f32_e32 v138, s2, v138
	v_add_f32_e32 v137, v137, v138
	v_fma_f32 v137, v137, s24, v12
	v_rsq_f32_e32 v137, v137
	s_mul_i32 s20, s68, 2
	s_add_i32 s20, s20, s70
	s_lshl_b32 s22, s20, 12
	s_mov_b32 s23, 0
	v_lshl_add_u64 v[10:11], v[8:9], 0, s[22:23]
	v_mul_f32_e32 v140, v120, v137
	v_mul_f32_e32 v141, v121, v137
	v_mul_f32_e32 v142, v122, v137
	v_mul_f32_e32 v143, v123, v137
	v_mul_f32_e32 v144, v124, v137
	v_mul_f32_e32 v145, v125, v137
	v_mul_f32_e32 v146, v126, v137
	v_mul_f32_e32 v147, v127, v137
	v_mul_f32_e32 v148, v128, v137
	v_mul_f32_e32 v149, v129, v137
	v_mul_f32_e32 v150, v130, v137
	v_mul_f32_e32 v151, v131, v137
	v_mul_f32_e32 v152, v132, v137
	v_mul_f32_e32 v153, v133, v137
	v_mul_f32_e32 v154, v134, v137
	v_mul_f32_e32 v155, v135, v137
	v_mul_f32_e32 v140, v140, v100
	v_mul_f32_e32 v141, v141, v101
	v_mul_f32_e32 v142, v142, v102
	v_mul_f32_e32 v143, v143, v103
	v_mul_f32_e32 v144, v144, v104
	v_mul_f32_e32 v145, v145, v105
	v_mul_f32_e32 v146, v146, v106
	v_mul_f32_e32 v147, v147, v107
	v_mul_f32_e32 v148, v148, v108
	v_mul_f32_e32 v149, v149, v109
	v_mul_f32_e32 v150, v150, v110
	v_mul_f32_e32 v151, v151, v111
	v_mul_f32_e32 v152, v152, v112
	v_mul_f32_e32 v153, v153, v113
	v_mul_f32_e32 v154, v154, v114
	v_mul_f32_e32 v155, v155, v115
	global_store_dwordx4 v[10:11], v[140:143], off
	global_store_dwordx4 v[10:11], v[144:147], off offset:1024
	global_store_dwordx4 v[10:11], v[148:151], off offset:2048
	global_store_dwordx4 v[10:11], v[152:155], off offset:3072
	s_waitcnt vmcnt(28)
	v_lshlrev_b32_e32 v120, 16, v44
	v_and_b32_e32 v121, 0xffff0000, v44
	v_lshlrev_b32_e32 v122, 16, v45
	v_and_b32_e32 v123, 0xffff0000, v45
	v_lshlrev_b32_e32 v124, 16, v46
	v_and_b32_e32 v125, 0xffff0000, v46
	v_lshlrev_b32_e32 v126, 16, v47
	v_and_b32_e32 v127, 0xffff0000, v47
	v_lshlrev_b32_e32 v128, 16, v48
	v_and_b32_e32 v129, 0xffff0000, v48
	v_lshlrev_b32_e32 v130, 16, v49
	v_and_b32_e32 v131, 0xffff0000, v49
	v_lshlrev_b32_e32 v132, 16, v50
	v_and_b32_e32 v133, 0xffff0000, v50
	v_lshlrev_b32_e32 v134, 16, v51
	v_and_b32_e32 v135, 0xffff0000, v51
	v_mul_f32_e32 v136, v120, v120
	v_mul_f32_e32 v137, v124, v124
	v_mul_f32_e32 v138, v128, v128
	v_mul_f32_e32 v139, v132, v132
	v_fmac_f32_e32 v136, v121, v121
	v_fmac_f32_e32 v137, v125, v125
	v_fmac_f32_e32 v138, v129, v129
	v_fmac_f32_e32 v139, v133, v133
	v_fmac_f32_e32 v136, v122, v122
	v_fmac_f32_e32 v137, v126, v126
	v_fmac_f32_e32 v138, v130, v130
	v_fmac_f32_e32 v139, v134, v134
	v_fmac_f32_e32 v136, v123, v123
	v_fmac_f32_e32 v137, v127, v127
	v_fmac_f32_e32 v138, v131, v131
	v_fmac_f32_e32 v139, v135, v135
	v_add_f32_e32 v136, v136, v137
	v_add_f32_e32 v138, v138, v139
	v_add_f32_e32 v136, v136, v138
	s_nop 1
	v_add_f32_dpp v136, v136, v136 quad_perm:[1,0,3,2] row_mask:0xf bank_mask:0xf bound_ctrl:1
	s_nop 1
	v_add_f32_dpp v136, v136, v136 quad_perm:[2,3,0,1] row_mask:0xf bank_mask:0xf bound_ctrl:1
	s_nop 1
	v_add_f32_dpp v136, v136, v136 row_ror:4 row_mask:0xf bank_mask:0xf bound_ctrl:1
	s_nop 1
	v_add_f32_dpp v136, v136, v136 row_ror:8 row_mask:0xf bank_mask:0xf bound_ctrl:1
	s_nop 1
	v_readlane_b32 s0, v136, 0
	v_readlane_b32 s1, v136, 16
	v_readlane_b32 s2, v136, 32
	v_readlane_b32 s3, v136, 48
	s_nop 1
	v_mov_b32_e32 v137, s1
	v_mov_b32_e32 v138, s3
	v_add_f32_e32 v137, s0, v137
	v_add_f32_e32 v138, s2, v138
	v_add_f32_e32 v137, v137, v138
	v_fma_f32 v137, v137, s24, v12
	v_rsq_f32_e32 v137, v137
	s_mul_i32 s20, s68, 3
	s_add_i32 s20, s20, s70
	s_lshl_b32 s22, s20, 12
	s_mov_b32 s23, 0
	v_lshl_add_u64 v[10:11], v[8:9], 0, s[22:23]
	v_mul_f32_e32 v140, v120, v137
	v_mul_f32_e32 v141, v121, v137
	v_mul_f32_e32 v142, v122, v137
	v_mul_f32_e32 v143, v123, v137
	v_mul_f32_e32 v144, v124, v137
	v_mul_f32_e32 v145, v125, v137
	v_mul_f32_e32 v146, v126, v137
	v_mul_f32_e32 v147, v127, v137
	v_mul_f32_e32 v148, v128, v137
	v_mul_f32_e32 v149, v129, v137
	v_mul_f32_e32 v150, v130, v137
	v_mul_f32_e32 v151, v131, v137
	v_mul_f32_e32 v152, v132, v137
	v_mul_f32_e32 v153, v133, v137
	v_mul_f32_e32 v154, v134, v137
	v_mul_f32_e32 v155, v135, v137
	v_mul_f32_e32 v140, v140, v100
	v_mul_f32_e32 v141, v141, v101
	v_mul_f32_e32 v142, v142, v102
	v_mul_f32_e32 v143, v143, v103
	v_mul_f32_e32 v144, v144, v104
	v_mul_f32_e32 v145, v145, v105
	v_mul_f32_e32 v146, v146, v106
	v_mul_f32_e32 v147, v147, v107
	v_mul_f32_e32 v148, v148, v108
	v_mul_f32_e32 v149, v149, v109
	v_mul_f32_e32 v150, v150, v110
	v_mul_f32_e32 v151, v151, v111
	v_mul_f32_e32 v152, v152, v112
	v_mul_f32_e32 v153, v153, v113
	v_mul_f32_e32 v154, v154, v114
	v_mul_f32_e32 v155, v155, v115
	global_store_dwordx4 v[10:11], v[140:143], off
	global_store_dwordx4 v[10:11], v[144:147], off offset:1024
	global_store_dwordx4 v[10:11], v[148:151], off offset:2048
	global_store_dwordx4 v[10:11], v[152:155], off offset:3072
	s_waitcnt vmcnt(28)
	v_lshlrev_b32_e32 v120, 16, v52
	v_and_b32_e32 v121, 0xffff0000, v52
	v_lshlrev_b32_e32 v122, 16, v53
	v_and_b32_e32 v123, 0xffff0000, v53
	v_lshlrev_b32_e32 v124, 16, v54
	v_and_b32_e32 v125, 0xffff0000, v54
	v_lshlrev_b32_e32 v126, 16, v55
	v_and_b32_e32 v127, 0xffff0000, v55
	v_lshlrev_b32_e32 v128, 16, v56
	v_and_b32_e32 v129, 0xffff0000, v56
	v_lshlrev_b32_e32 v130, 16, v57
	v_and_b32_e32 v131, 0xffff0000, v57
	v_lshlrev_b32_e32 v132, 16, v58
	v_and_b32_e32 v133, 0xffff0000, v58
	v_lshlrev_b32_e32 v134, 16, v59
	v_and_b32_e32 v135, 0xffff0000, v59
	v_mul_f32_e32 v136, v120, v120
	v_mul_f32_e32 v137, v124, v124
	v_mul_f32_e32 v138, v128, v128
	v_mul_f32_e32 v139, v132, v132
	v_fmac_f32_e32 v136, v121, v121
	v_fmac_f32_e32 v137, v125, v125
	v_fmac_f32_e32 v138, v129, v129
	v_fmac_f32_e32 v139, v133, v133
	v_fmac_f32_e32 v136, v122, v122
	v_fmac_f32_e32 v137, v126, v126
	v_fmac_f32_e32 v138, v130, v130
	v_fmac_f32_e32 v139, v134, v134
	v_fmac_f32_e32 v136, v123, v123
	v_fmac_f32_e32 v137, v127, v127
	v_fmac_f32_e32 v138, v131, v131
	v_fmac_f32_e32 v139, v135, v135
	v_add_f32_e32 v136, v136, v137
	v_add_f32_e32 v138, v138, v139
	v_add_f32_e32 v136, v136, v138
	s_nop 1
	v_add_f32_dpp v136, v136, v136 quad_perm:[1,0,3,2] row_mask:0xf bank_mask:0xf bound_ctrl:1
	s_nop 1
	v_add_f32_dpp v136, v136, v136 quad_perm:[2,3,0,1] row_mask:0xf bank_mask:0xf bound_ctrl:1
	s_nop 1
	v_add_f32_dpp v136, v136, v136 row_ror:4 row_mask:0xf bank_mask:0xf bound_ctrl:1
	s_nop 1
	v_add_f32_dpp v136, v136, v136 row_ror:8 row_mask:0xf bank_mask:0xf bound_ctrl:1
	s_nop 1
	v_readlane_b32 s0, v136, 0
	v_readlane_b32 s1, v136, 16
	v_readlane_b32 s2, v136, 32
	v_readlane_b32 s3, v136, 48
	s_nop 1
	v_mov_b32_e32 v137, s1
	v_mov_b32_e32 v138, s3
	v_add_f32_e32 v137, s0, v137
	v_add_f32_e32 v138, s2, v138
	v_add_f32_e32 v137, v137, v138
	v_fma_f32 v137, v137, s24, v12
	v_rsq_f32_e32 v137, v137
	s_mul_i32 s20, s68, 4
	s_add_i32 s20, s20, s70
	s_lshl_b32 s22, s20, 12
	s_mov_b32 s23, 0
	v_lshl_add_u64 v[10:11], v[8:9], 0, s[22:23]
	v_mul_f32_e32 v140, v120, v137
	v_mul_f32_e32 v141, v121, v137
	v_mul_f32_e32 v142, v122, v137
	v_mul_f32_e32 v143, v123, v137
	v_mul_f32_e32 v144, v124, v137
	v_mul_f32_e32 v145, v125, v137
	v_mul_f32_e32 v146, v126, v137
	v_mul_f32_e32 v147, v127, v137
	v_mul_f32_e32 v148, v128, v137
	v_mul_f32_e32 v149, v129, v137
	v_mul_f32_e32 v150, v130, v137
	v_mul_f32_e32 v151, v131, v137
	v_mul_f32_e32 v152, v132, v137
	v_mul_f32_e32 v153, v133, v137
	v_mul_f32_e32 v154, v134, v137
	v_mul_f32_e32 v155, v135, v137
	v_mul_f32_e32 v140, v140, v100
	v_mul_f32_e32 v141, v141, v101
	v_mul_f32_e32 v142, v142, v102
	v_mul_f32_e32 v143, v143, v103
	v_mul_f32_e32 v144, v144, v104
	v_mul_f32_e32 v145, v145, v105
	v_mul_f32_e32 v146, v146, v106
	v_mul_f32_e32 v147, v147, v107
	v_mul_f32_e32 v148, v148, v108
	v_mul_f32_e32 v149, v149, v109
	v_mul_f32_e32 v150, v150, v110
	v_mul_f32_e32 v151, v151, v111
	v_mul_f32_e32 v152, v152, v112
	v_mul_f32_e32 v153, v153, v113
	v_mul_f32_e32 v154, v154, v114
	v_mul_f32_e32 v155, v155, v115
	global_store_dwordx4 v[10:11], v[140:143], off
	global_store_dwordx4 v[10:11], v[144:147], off offset:1024
	global_store_dwordx4 v[10:11], v[148:151], off offset:2048
	global_store_dwordx4 v[10:11], v[152:155], off offset:3072
	s_waitcnt vmcnt(28)
	v_lshlrev_b32_e32 v120, 16, v60
	v_and_b32_e32 v121, 0xffff0000, v60
	v_lshlrev_b32_e32 v122, 16, v61
	v_and_b32_e32 v123, 0xffff0000, v61
	v_lshlrev_b32_e32 v124, 16, v62
	v_and_b32_e32 v125, 0xffff0000, v62
	v_lshlrev_b32_e32 v126, 16, v63
	v_and_b32_e32 v127, 0xffff0000, v63
	v_lshlrev_b32_e32 v128, 16, v64
	v_and_b32_e32 v129, 0xffff0000, v64
	v_lshlrev_b32_e32 v130, 16, v65
	v_and_b32_e32 v131, 0xffff0000, v65
	v_lshlrev_b32_e32 v132, 16, v66
	v_and_b32_e32 v133, 0xffff0000, v66
	v_lshlrev_b32_e32 v134, 16, v67
	v_and_b32_e32 v135, 0xffff0000, v67
	v_mul_f32_e32 v136, v120, v120
	v_mul_f32_e32 v137, v124, v124
	v_mul_f32_e32 v138, v128, v128
	v_mul_f32_e32 v139, v132, v132
	v_fmac_f32_e32 v136, v121, v121
	v_fmac_f32_e32 v137, v125, v125
	v_fmac_f32_e32 v138, v129, v129
	v_fmac_f32_e32 v139, v133, v133
	v_fmac_f32_e32 v136, v122, v122
	v_fmac_f32_e32 v137, v126, v126
	v_fmac_f32_e32 v138, v130, v130
	v_fmac_f32_e32 v139, v134, v134
	v_fmac_f32_e32 v136, v123, v123
	v_fmac_f32_e32 v137, v127, v127
	v_fmac_f32_e32 v138, v131, v131
	v_fmac_f32_e32 v139, v135, v135
	v_add_f32_e32 v136, v136, v137
	v_add_f32_e32 v138, v138, v139
	v_add_f32_e32 v136, v136, v138
	s_nop 1
	v_add_f32_dpp v136, v136, v136 quad_perm:[1,0,3,2] row_mask:0xf bank_mask:0xf bound_ctrl:1
	s_nop 1
	v_add_f32_dpp v136, v136, v136 quad_perm:[2,3,0,1] row_mask:0xf bank_mask:0xf bound_ctrl:1
	s_nop 1
	v_add_f32_dpp v136, v136, v136 row_ror:4 row_mask:0xf bank_mask:0xf bound_ctrl:1
	s_nop 1
	v_add_f32_dpp v136, v136, v136 row_ror:8 row_mask:0xf bank_mask:0xf bound_ctrl:1
	s_nop 1
	v_readlane_b32 s0, v136, 0
	v_readlane_b32 s1, v136, 16
	v_readlane_b32 s2, v136, 32
	v_readlane_b32 s3, v136, 48
	s_nop 1
	v_mov_b32_e32 v137, s1
	v_mov_b32_e32 v138, s3
	v_add_f32_e32 v137, s0, v137
	v_add_f32_e32 v138, s2, v138
	v_add_f32_e32 v137, v137, v138
	v_fma_f32 v137, v137, s24, v12
	v_rsq_f32_e32 v137, v137
	s_mul_i32 s20, s68, 5
	s_add_i32 s20, s20, s70
	s_lshl_b32 s22, s20, 12
	s_mov_b32 s23, 0
	v_lshl_add_u64 v[10:11], v[8:9], 0, s[22:23]
	v_mul_f32_e32 v140, v120, v137
	v_mul_f32_e32 v141, v121, v137
	v_mul_f32_e32 v142, v122, v137
	v_mul_f32_e32 v143, v123, v137
	v_mul_f32_e32 v144, v124, v137
	v_mul_f32_e32 v145, v125, v137
	v_mul_f32_e32 v146, v126, v137
	v_mul_f32_e32 v147, v127, v137
	v_mul_f32_e32 v148, v128, v137
	v_mul_f32_e32 v149, v129, v137
	v_mul_f32_e32 v150, v130, v137
	v_mul_f32_e32 v151, v131, v137
	v_mul_f32_e32 v152, v132, v137
	v_mul_f32_e32 v153, v133, v137
	v_mul_f32_e32 v154, v134, v137
	v_mul_f32_e32 v155, v135, v137
	v_mul_f32_e32 v140, v140, v100
	v_mul_f32_e32 v141, v141, v101
	v_mul_f32_e32 v142, v142, v102
	v_mul_f32_e32 v143, v143, v103
	v_mul_f32_e32 v144, v144, v104
	v_mul_f32_e32 v145, v145, v105
	v_mul_f32_e32 v146, v146, v106
	v_mul_f32_e32 v147, v147, v107
	v_mul_f32_e32 v148, v148, v108
	v_mul_f32_e32 v149, v149, v109
	v_mul_f32_e32 v150, v150, v110
	v_mul_f32_e32 v151, v151, v111
	v_mul_f32_e32 v152, v152, v112
	v_mul_f32_e32 v153, v153, v113
	v_mul_f32_e32 v154, v154, v114
	v_mul_f32_e32 v155, v155, v115
	global_store_dwordx4 v[10:11], v[140:143], off
	global_store_dwordx4 v[10:11], v[144:147], off offset:1024
	global_store_dwordx4 v[10:11], v[148:151], off offset:2048
	global_store_dwordx4 v[10:11], v[152:155], off offset:3072
	s_waitcnt vmcnt(28)
	v_lshlrev_b32_e32 v120, 16, v68
	v_and_b32_e32 v121, 0xffff0000, v68
	v_lshlrev_b32_e32 v122, 16, v69
	v_and_b32_e32 v123, 0xffff0000, v69
	v_lshlrev_b32_e32 v124, 16, v70
	v_and_b32_e32 v125, 0xffff0000, v70
	v_lshlrev_b32_e32 v126, 16, v71
	v_and_b32_e32 v127, 0xffff0000, v71
	v_lshlrev_b32_e32 v128, 16, v72
	v_and_b32_e32 v129, 0xffff0000, v72
	v_lshlrev_b32_e32 v130, 16, v73
	v_and_b32_e32 v131, 0xffff0000, v73
	v_lshlrev_b32_e32 v132, 16, v74
	v_and_b32_e32 v133, 0xffff0000, v74
	v_lshlrev_b32_e32 v134, 16, v75
	v_and_b32_e32 v135, 0xffff0000, v75
	v_mul_f32_e32 v136, v120, v120
	v_mul_f32_e32 v137, v124, v124
	v_mul_f32_e32 v138, v128, v128
	v_mul_f32_e32 v139, v132, v132
	v_fmac_f32_e32 v136, v121, v121
	v_fmac_f32_e32 v137, v125, v125
	v_fmac_f32_e32 v138, v129, v129
	v_fmac_f32_e32 v139, v133, v133
	v_fmac_f32_e32 v136, v122, v122
	v_fmac_f32_e32 v137, v126, v126
	v_fmac_f32_e32 v138, v130, v130
	v_fmac_f32_e32 v139, v134, v134
	v_fmac_f32_e32 v136, v123, v123
	v_fmac_f32_e32 v137, v127, v127
	v_fmac_f32_e32 v138, v131, v131
	v_fmac_f32_e32 v139, v135, v135
	v_add_f32_e32 v136, v136, v137
	v_add_f32_e32 v138, v138, v139
	v_add_f32_e32 v136, v136, v138
	s_nop 1
	v_add_f32_dpp v136, v136, v136 quad_perm:[1,0,3,2] row_mask:0xf bank_mask:0xf bound_ctrl:1
	s_nop 1
	v_add_f32_dpp v136, v136, v136 quad_perm:[2,3,0,1] row_mask:0xf bank_mask:0xf bound_ctrl:1
	s_nop 1
	v_add_f32_dpp v136, v136, v136 row_ror:4 row_mask:0xf bank_mask:0xf bound_ctrl:1
	s_nop 1
	v_add_f32_dpp v136, v136, v136 row_ror:8 row_mask:0xf bank_mask:0xf bound_ctrl:1
	s_nop 1
	v_readlane_b32 s0, v136, 0
	v_readlane_b32 s1, v136, 16
	v_readlane_b32 s2, v136, 32
	v_readlane_b32 s3, v136, 48
	s_nop 1
	v_mov_b32_e32 v137, s1
	v_mov_b32_e32 v138, s3
	v_add_f32_e32 v137, s0, v137
	v_add_f32_e32 v138, s2, v138
	v_add_f32_e32 v137, v137, v138
	v_fma_f32 v137, v137, s24, v12
	v_rsq_f32_e32 v137, v137
	s_mul_i32 s20, s68, 6
	s_add_i32 s20, s20, s70
	s_lshl_b32 s22, s20, 12
	s_mov_b32 s23, 0
	v_lshl_add_u64 v[10:11], v[8:9], 0, s[22:23]
	v_mul_f32_e32 v140, v120, v137
	v_mul_f32_e32 v141, v121, v137
	v_mul_f32_e32 v142, v122, v137
	v_mul_f32_e32 v143, v123, v137
	v_mul_f32_e32 v144, v124, v137
	v_mul_f32_e32 v145, v125, v137
	v_mul_f32_e32 v146, v126, v137
	v_mul_f32_e32 v147, v127, v137
	v_mul_f32_e32 v148, v128, v137
	v_mul_f32_e32 v149, v129, v137
	v_mul_f32_e32 v150, v130, v137
	v_mul_f32_e32 v151, v131, v137
	v_mul_f32_e32 v152, v132, v137
	v_mul_f32_e32 v153, v133, v137
	v_mul_f32_e32 v154, v134, v137
	v_mul_f32_e32 v155, v135, v137
	v_mul_f32_e32 v140, v140, v100
	v_mul_f32_e32 v141, v141, v101
	v_mul_f32_e32 v142, v142, v102
	v_mul_f32_e32 v143, v143, v103
	v_mul_f32_e32 v144, v144, v104
	v_mul_f32_e32 v145, v145, v105
	v_mul_f32_e32 v146, v146, v106
	v_mul_f32_e32 v147, v147, v107
	v_mul_f32_e32 v148, v148, v108
	v_mul_f32_e32 v149, v149, v109
	v_mul_f32_e32 v150, v150, v110
	v_mul_f32_e32 v151, v151, v111
	v_mul_f32_e32 v152, v152, v112
	v_mul_f32_e32 v153, v153, v113
	v_mul_f32_e32 v154, v154, v114
	v_mul_f32_e32 v155, v155, v115
	global_store_dwordx4 v[10:11], v[140:143], off
	global_store_dwordx4 v[10:11], v[144:147], off offset:1024
	global_store_dwordx4 v[10:11], v[148:151], off offset:2048
	global_store_dwordx4 v[10:11], v[152:155], off offset:3072
	s_waitcnt vmcnt(28)
	v_lshlrev_b32_e32 v120, 16, v76
	v_and_b32_e32 v121, 0xffff0000, v76
	v_lshlrev_b32_e32 v122, 16, v77
	v_and_b32_e32 v123, 0xffff0000, v77
	v_lshlrev_b32_e32 v124, 16, v78
	v_and_b32_e32 v125, 0xffff0000, v78
	v_lshlrev_b32_e32 v126, 16, v79
	v_and_b32_e32 v127, 0xffff0000, v79
	v_lshlrev_b32_e32 v128, 16, v80
	v_and_b32_e32 v129, 0xffff0000, v80
	v_lshlrev_b32_e32 v130, 16, v81
	v_and_b32_e32 v131, 0xffff0000, v81
	v_lshlrev_b32_e32 v132, 16, v82
	v_and_b32_e32 v133, 0xffff0000, v82
	v_lshlrev_b32_e32 v134, 16, v83
	v_and_b32_e32 v135, 0xffff0000, v83
	v_mul_f32_e32 v136, v120, v120
	v_mul_f32_e32 v137, v124, v124
	v_mul_f32_e32 v138, v128, v128
	v_mul_f32_e32 v139, v132, v132
	v_fmac_f32_e32 v136, v121, v121
	v_fmac_f32_e32 v137, v125, v125
	v_fmac_f32_e32 v138, v129, v129
	v_fmac_f32_e32 v139, v133, v133
	v_fmac_f32_e32 v136, v122, v122
	v_fmac_f32_e32 v137, v126, v126
	v_fmac_f32_e32 v138, v130, v130
	v_fmac_f32_e32 v139, v134, v134
	v_fmac_f32_e32 v136, v123, v123
	v_fmac_f32_e32 v137, v127, v127
	v_fmac_f32_e32 v138, v131, v131
	v_fmac_f32_e32 v139, v135, v135
	v_add_f32_e32 v136, v136, v137
	v_add_f32_e32 v138, v138, v139
	v_add_f32_e32 v136, v136, v138
	s_nop 1
	v_add_f32_dpp v136, v136, v136 quad_perm:[1,0,3,2] row_mask:0xf bank_mask:0xf bound_ctrl:1
	s_nop 1
	v_add_f32_dpp v136, v136, v136 quad_perm:[2,3,0,1] row_mask:0xf bank_mask:0xf bound_ctrl:1
	s_nop 1
	v_add_f32_dpp v136, v136, v136 row_ror:4 row_mask:0xf bank_mask:0xf bound_ctrl:1
	s_nop 1
	v_add_f32_dpp v136, v136, v136 row_ror:8 row_mask:0xf bank_mask:0xf bound_ctrl:1
	s_nop 1
	v_readlane_b32 s0, v136, 0
	v_readlane_b32 s1, v136, 16
	v_readlane_b32 s2, v136, 32
	v_readlane_b32 s3, v136, 48
	s_nop 1
	v_mov_b32_e32 v137, s1
	v_mov_b32_e32 v138, s3
	v_add_f32_e32 v137, s0, v137
	v_add_f32_e32 v138, s2, v138
	v_add_f32_e32 v137, v137, v138
	v_fma_f32 v137, v137, s24, v12
	v_rsq_f32_e32 v137, v137
	s_mul_i32 s20, s68, 7
	s_add_i32 s20, s20, s70
	s_lshl_b32 s22, s20, 12
	s_mov_b32 s23, 0
	v_lshl_add_u64 v[10:11], v[8:9], 0, s[22:23]
	v_mul_f32_e32 v140, v120, v137
	v_mul_f32_e32 v141, v121, v137
	v_mul_f32_e32 v142, v122, v137
	v_mul_f32_e32 v143, v123, v137
	v_mul_f32_e32 v144, v124, v137
	v_mul_f32_e32 v145, v125, v137
	v_mul_f32_e32 v146, v126, v137
	v_mul_f32_e32 v147, v127, v137
	v_mul_f32_e32 v148, v128, v137
	v_mul_f32_e32 v149, v129, v137
	v_mul_f32_e32 v150, v130, v137
	v_mul_f32_e32 v151, v131, v137
	v_mul_f32_e32 v152, v132, v137
	v_mul_f32_e32 v153, v133, v137
	v_mul_f32_e32 v154, v134, v137
	v_mul_f32_e32 v155, v135, v137
	v_mul_f32_e32 v140, v140, v100
	v_mul_f32_e32 v141, v141, v101
	v_mul_f32_e32 v142, v142, v102
	v_mul_f32_e32 v143, v143, v103
	v_mul_f32_e32 v144, v144, v104
	v_mul_f32_e32 v145, v145, v105
	v_mul_f32_e32 v146, v146, v106
	v_mul_f32_e32 v147, v147, v107
	v_mul_f32_e32 v148, v148, v108
	v_mul_f32_e32 v149, v149, v109
	v_mul_f32_e32 v150, v150, v110
	v_mul_f32_e32 v151, v151, v111
	v_mul_f32_e32 v152, v152, v112
	v_mul_f32_e32 v153, v153, v113
	v_mul_f32_e32 v154, v154, v114
	v_mul_f32_e32 v155, v155, v115
	global_store_dwordx4 v[10:11], v[140:143], off
	global_store_dwordx4 v[10:11], v[144:147], off offset:1024
	global_store_dwordx4 v[10:11], v[148:151], off offset:2048
	global_store_dwordx4 v[10:11], v[152:155], off offset:3072
	s_cmpk_lt_i32 s70, 0x400
	s_cbranch_scc0 .LBB0_1553
	s_waitcnt vmcnt(32)
	v_lshlrev_b32_e32 v120, 16, v84
	v_and_b32_e32 v121, 0xffff0000, v84
	v_lshlrev_b32_e32 v122, 16, v85
	v_and_b32_e32 v123, 0xffff0000, v85
	v_lshlrev_b32_e32 v124, 16, v86
	v_and_b32_e32 v125, 0xffff0000, v86
	v_lshlrev_b32_e32 v126, 16, v87
	v_and_b32_e32 v127, 0xffff0000, v87
	v_lshlrev_b32_e32 v128, 16, v88
	v_and_b32_e32 v129, 0xffff0000, v88
	v_lshlrev_b32_e32 v130, 16, v89
	v_and_b32_e32 v131, 0xffff0000, v89
	v_lshlrev_b32_e32 v132, 16, v90
	v_and_b32_e32 v133, 0xffff0000, v90
	v_lshlrev_b32_e32 v134, 16, v91
	v_and_b32_e32 v135, 0xffff0000, v91
	v_mul_f32_e32 v136, v120, v120
	v_mul_f32_e32 v137, v124, v124
	v_mul_f32_e32 v138, v128, v128
	v_mul_f32_e32 v139, v132, v132
	v_fmac_f32_e32 v136, v121, v121
	v_fmac_f32_e32 v137, v125, v125
	v_fmac_f32_e32 v138, v129, v129
	v_fmac_f32_e32 v139, v133, v133
	v_fmac_f32_e32 v136, v122, v122
	v_fmac_f32_e32 v137, v126, v126
	v_fmac_f32_e32 v138, v130, v130
	v_fmac_f32_e32 v139, v134, v134
	v_fmac_f32_e32 v136, v123, v123
	v_fmac_f32_e32 v137, v127, v127
	v_fmac_f32_e32 v138, v131, v131
	v_fmac_f32_e32 v139, v135, v135
	v_add_f32_e32 v136, v136, v137
	v_add_f32_e32 v138, v138, v139
	v_add_f32_e32 v136, v136, v138
	s_nop 1
	v_add_f32_dpp v136, v136, v136 quad_perm:[1,0,3,2] row_mask:0xf bank_mask:0xf bound_ctrl:1
	s_nop 1
	v_add_f32_dpp v136, v136, v136 quad_perm:[2,3,0,1] row_mask:0xf bank_mask:0xf bound_ctrl:1
	s_nop 1
	v_add_f32_dpp v136, v136, v136 row_ror:4 row_mask:0xf bank_mask:0xf bound_ctrl:1
	s_nop 1
	v_add_f32_dpp v136, v136, v136 row_ror:8 row_mask:0xf bank_mask:0xf bound_ctrl:1
	s_nop 1
	v_readlane_b32 s0, v136, 0
	v_readlane_b32 s1, v136, 16
	v_readlane_b32 s2, v136, 32
	v_readlane_b32 s3, v136, 48
	s_nop 1
	v_mov_b32_e32 v137, s1
	v_mov_b32_e32 v138, s3
	v_add_f32_e32 v137, s0, v137
	v_add_f32_e32 v138, s2, v138
	v_add_f32_e32 v137, v137, v138
	v_fma_f32 v137, v137, s24, v12
	v_rsq_f32_e32 v137, v137
	s_mul_i32 s20, s68, 8
	s_add_i32 s20, s20, s70
	s_lshl_b32 s22, s20, 12
	s_mov_b32 s23, 0
	v_lshl_add_u64 v[10:11], v[8:9], 0, s[22:23]
	v_mul_f32_e32 v140, v120, v137
	v_mul_f32_e32 v141, v121, v137
	v_mul_f32_e32 v142, v122, v137
	v_mul_f32_e32 v143, v123, v137
	v_mul_f32_e32 v144, v124, v137
	v_mul_f32_e32 v145, v125, v137
	v_mul_f32_e32 v146, v126, v137
	v_mul_f32_e32 v147, v127, v137
	v_mul_f32_e32 v148, v128, v137
	v_mul_f32_e32 v149, v129, v137
	v_mul_f32_e32 v150, v130, v137
	v_mul_f32_e32 v151, v131, v137
	v_mul_f32_e32 v152, v132, v137
	v_mul_f32_e32 v153, v133, v137
	v_mul_f32_e32 v154, v134, v137
	v_mul_f32_e32 v155, v135, v137
	v_mul_f32_e32 v140, v140, v100
	v_mul_f32_e32 v141, v141, v101
	v_mul_f32_e32 v142, v142, v102
	v_mul_f32_e32 v143, v143, v103
	v_mul_f32_e32 v144, v144, v104
	v_mul_f32_e32 v145, v145, v105
	v_mul_f32_e32 v146, v146, v106
	v_mul_f32_e32 v147, v147, v107
	v_mul_f32_e32 v148, v148, v108
	v_mul_f32_e32 v149, v149, v109
	v_mul_f32_e32 v150, v150, v110
	v_mul_f32_e32 v151, v151, v111
	v_mul_f32_e32 v152, v152, v112
	v_mul_f32_e32 v153, v153, v113
	v_mul_f32_e32 v154, v154, v114
	v_mul_f32_e32 v155, v155, v115
	global_store_dwordx4 v[10:11], v[140:143], off
	global_store_dwordx4 v[10:11], v[144:147], off offset:1024
	global_store_dwordx4 v[10:11], v[148:151], off offset:2048
	global_store_dwordx4 v[10:11], v[152:155], off offset:3072
	s_branch .LBB0_1553
.Lp8_orig:
	v_mov_b32_e32 v179, 0
	v_readlane_b32 s0, v250, 60
	v_mov_b32_e32 v177, v179
	v_readlane_b32 s2, v250, 62
	v_readlane_b32 s3, v250, 63
	v_readlane_b32 s12, v249, 8
	v_readlane_b32 s13, v249, 9
	v_readlane_b32 s14, v249, 10
	v_readlane_b32 s15, v249, 11
	v_lshl_add_u64 v[4:5], s[16:17], 0, v[178:179]
	v_lshl_add_u64 v[6:7], s[12:13], 0, v[176:177]
	v_lshl_add_u64 v[8:9], s[14:15], 0, v[176:177]
	s_mov_b32 s2, 0x3a800000
	v_mov_b32_e32 v10, 0x358637bd
	s_mov_b32 s3, 0x800000
	v_readlane_b32 s1, v250, 61
	v_readlane_b32 s4, v249, 0
	v_readlane_b32 s5, v249, 1
	v_readlane_b32 s6, v249, 2
	v_readlane_b32 s7, v249, 3
	v_readlane_b32 s8, v249, 4
	v_readlane_b32 s9, v249, 5
	v_readlane_b32 s10, v249, 6
	v_readlane_b32 s11, v249, 7
	s_branch .LBB0_1545
